# v4 attention + weight-transpose item loads issued together + LayerNorm context-row loads hoisted (counted vmcnt)
# speedup vs baseline: 1.0348x; 1.0114x over previous
; DI float hlo(unsigned u) { return (float)__builtin_bit_cast(f16x2_t, u).x; }
; DI float hhi(unsigned u) { return (float)__builtin_bit_cast(f16x2_t, u).y; }
; DI void lnmod_phase(const Args& A, LAS unsigned char* lds, int tid, int bid, int G, bool init, int l_norm, int i_norm, int l_mod, int i_mod, bool want_dt, int nrows, bool ctx_partial, const float* gprev, const float* bprev) {
;     ...
;         for (int j = 0; j < 4; ++j) v[j] = init ? fn[j] : (f32x4){hlo(un[j].x), hhi(un[j].x), hlo(un[j].y), hhi(un[j].y)};
;         { const int rown = row + G * 8;
;           if (rown < nrows) {
;               if (init) { const float* xin = rown < M_LAT ? A.in[I_X] + (size_t)rown * DM : A.in[I_CTX] + (size_t)(rown - M_LAT) * DM;
; #pragma unroll
;                   for (int j = 0; j < 4; ++j) fn[j] = *(const f32x4*)(xin + 256 * j + 4 * lane); }
;               else {
; #pragma unroll
;                   for (int j = 0; j < 4; ++j) un[j] = *(const u32x2*)(X16 + (size_t)rown * DM + 256 * j + 4 * lane); } } }
;         f32x2* STAT = (f32x2*)(A.ws + WS_STAT);
;         if (ctx_partial && row >= M_LAT) {
.LBB0_207:
	s_or_b64 exec, exec, s[6:7]
	v_cvt_f32_f16_sdwa v106, v92 dst_sel:DWORD dst_unused:UNUSED_PAD src0_sel:WORD_1
	v_cvt_f32_f16_e32 v90, v92
	v_cvt_f32_f16_sdwa v91, v93 dst_sel:DWORD dst_unused:UNUSED_PAD src0_sel:WORD_1
	v_cvt_f32_f16_e32 v107, v93
	v_cvt_f32_f16_sdwa v102, v94 dst_sel:DWORD dst_unused:UNUSED_PAD src0_sel:WORD_1
	v_cvt_f32_f16_e32 v92, v94
	v_cvt_f32_f16_sdwa v93, v95 dst_sel:DWORD dst_unused:UNUSED_PAD src0_sel:WORD_1
	v_cvt_f32_f16_e32 v103, v95
	v_cvt_f32_f16_sdwa v97, v98 dst_sel:DWORD dst_unused:UNUSED_PAD src0_sel:WORD_1
	v_cvt_f32_f16_e32 v96, v98
	v_cvt_f32_f16_sdwa v95, v99 dst_sel:DWORD dst_unused:UNUSED_PAD src0_sel:WORD_1
	v_cvt_f32_f16_e32 v94, v99
	v_cvt_f32_f16_sdwa v104, v88 dst_sel:DWORD dst_unused:UNUSED_PAD src0_sel:WORD_1
	v_cvt_f32_f16_e32 v100, v88
	v_cvt_f32_f16_sdwa v108, v89 dst_sel:DWORD dst_unused:UNUSED_PAD src0_sel:WORD_1
	v_cvt_f32_f16_e32 v98, v89
	v_readlane_b32 s36, v253, 23
	s_movk_i32 s6, 0x7fff
	v_readlane_b32 s38, v253, 25
	v_readlane_b32 s39, v253, 26
	v_cmp_lt_i32_e32 vcc, s6, v86
	v_readlane_b32 s37, v253, 24
	v_lshl_add_u64 v[88:89], s[38:39], 0, v[64:65]
	s_and_saveexec_b64 s[6:7], vcc
	s_cbranch_execz .LBB0_209
; DI unsigned pkh2(float lo, float hi) { return __builtin_bit_cast(unsigned, __builtin_amdgcn_cvt_pkrtz(lo, hi)); }
; DI void lnmod_phase(const Args& A, LAS unsigned char* lds, int tid, int bid, int G, bool init, int l_norm, int i_norm, int l_mod, int i_mod, bool want_dt, int nrows, bool ctx_partial, const float* gprev, const float* bprev) {
;     ...
;         if (ctx_partial && row >= M_LAT) {
;             { const f32x2 st = STAT[row];
; #pragma unroll
;               for (int j = 0; j < 4; ++j) v[j] = (v[j] - st.x) * st.y * *(const f32x4*)(gprev + 256 * j + 4 * lane) + *(const f32x4*)(bprev + 256 * j + 4 * lane); }
;             const float* t0 = (const float*)(A.ws + WS_T) + (size_t)(row - M_LAT) * DM; const float* t1 = t0 + (size_t)M_CTX * DM; const float* t2 = t1 + (size_t)M_CTX * DM; const float* t3 = t2 + (size_t)M_CTX * DM;
; #pragma unroll
;             for (int j = 0; j < 4; ++j) { v[j] = v[j] * ALPHA + (*(const f32x4*)(t0 + 256 * j + 4 * lane) + *(const f32x4*)(t1 + 256 * j + 4 * lane)) + (*(const f32x4*)(t2 + 256 * j + 4 * lane) + *(const f32x4*)(t3 + 256 * j + 4 * lane)); u32x2 w_; w_.x = pkh2(v[j].x, v[j].y); w_.y = pkh2(v[j].z, v[j].w); *(u32x2*)(xout + 256 * j + 4 * lane) = w_; }
;         }
	v_readlane_b32 s38, v253, 25
	v_readlane_b32 s39, v253, 26
	v_add_u32_e32 v146, 0xffff8000, v86
	s_nop 1
	v_lshl_add_u64 v[110:111], s[38:39], 0, v[74:75]
	global_load_dwordx2 v[122:123], v[110:111], off
	v_readlane_b32 s36, v251, 61
	v_readlane_b32 s37, v251, 62
	s_mov_b32 s19, 0x800000
	global_load_dwordx4 v[172:175], v[68:69], off
	global_load_dwordx4 v[118:121], v[70:71], off
	global_load_dwordx4 v[176:179], v[68:69], off offset:1024
	global_load_dwordx4 v[180:183], v[70:71], off offset:1024
	global_load_dwordx4 v[184:187], v[68:69], off offset:2048
	global_load_dwordx4 v[188:191], v[70:71], off offset:2048
	global_load_dwordx4 v[192:195], v[68:69], off offset:3072
	global_load_dwordx4 v[196:199], v[70:71], off offset:3072
	s_waitcnt vmcnt(8)
	v_sub_f32_e32 v111, v106, v122
	v_sub_f32_e32 v110, v90, v122
	v_sub_f32_e32 v90, v107, v122
	v_pk_mul_f32 v[106:107], v[122:123], v[110:111] op_sel:[1,0]
	v_sub_f32_e32 v91, v91, v122
	v_pk_mul_f32 v[90:91], v[122:123], v[90:91] op_sel:[1,0]
	v_sub_f32_e32 v93, v93, v122
	v_sub_f32_e32 v97, v97, v122
	v_sub_f32_e32 v96, v96, v122
	v_sub_f32_e32 v95, v95, v122
	v_sub_f32_e32 v94, v94, v122
	v_sub_f32_e32 v101, v104, v122
	v_sub_f32_e32 v100, v100, v122
	v_sub_f32_e32 v99, v108, v122
	v_sub_f32_e32 v98, v98, v122
	v_pk_mul_f32 v[108:109], v[122:123], v[100:101] op_sel:[1,0]
	s_waitcnt vmcnt(6)
	v_pk_fma_f32 v[126:127], v[172:173], v[106:107], v[118:119]
	v_pk_fma_f32 v[90:91], v[174:175], v[90:91], v[120:121]
	v_sub_f32_e32 v107, v102, v122
	v_sub_f32_e32 v106, v92, v122
	v_sub_f32_e32 v92, v103, v122
	v_pk_mul_f32 v[102:103], v[122:123], v[92:93] op_sel:[1,0]
	v_pk_mul_f32 v[92:93], v[122:123], v[106:107] op_sel:[1,0]
	v_pk_mul_f32 v[106:107], v[122:123], v[96:97] op_sel:[1,0]
	s_waitcnt vmcnt(4)
	v_pk_fma_f32 v[92:93], v[92:93], v[176:177], v[180:181]
	v_pk_fma_f32 v[110:111], v[102:103], v[178:179], v[182:183]
	v_pk_mul_f32 v[102:103], v[122:123], v[94:95] op_sel:[1,0]
	s_waitcnt vmcnt(2)
	v_pk_fma_f32 v[184:185], v[106:107], v[184:185], v[188:189]
	v_pk_fma_f32 v[186:187], v[102:103], v[186:187], v[190:191]
	v_pk_mul_f32 v[106:107], v[122:123], v[98:99] op_sel:[1,0]
	s_waitcnt vmcnt(0)
	v_pk_fma_f32 v[192:193], v[108:109], v[192:193], v[196:197]
	v_lshlrev_b64 v[102:103], 12, v[146:147]
	v_lshl_add_u64 v[102:103], s[36:37], 0, v[102:103]
	v_lshlrev_b32_e32 v146, 2, v66
	v_lshl_add_u64 v[108:109], v[102:103], 0, v[146:147]
	v_add_co_u32_e32 v172, vcc, s19, v108
	global_load_dwordx4 v[118:121], v[108:109], off
	s_nop 1
	v_addc_co_u32_e32 v173, vcc, 0, v109, vcc
	global_load_dwordx4 v[122:125], v[172:173], off
	s_mov_b64 s[36:37], 0x800000
	v_lshl_add_u64 v[112:113], v[108:109], 0, s[36:37]
	s_mov_b64 s[36:37], 0x1000000
	v_lshl_add_u64 v[174:175], v[108:109], 0, s[36:37]
	s_mov_b64 s[36:37], 0x1800000
	v_lshl_add_u64 v[176:177], v[108:109], 0, s[36:37]
	s_mov_b32 s19, 0x1000000
	v_add_co_u32_e32 v178, vcc, s19, v108
	s_mov_b32 s19, 0x1800000
	s_nop 1
	v_addc_co_u32_e32 v179, vcc, 0, v109, vcc
	global_load_dwordx4 v[180:183], v[178:179], off
	v_add_co_u32_e32 v188, vcc, s19, v108
	s_nop 1
	v_addc_co_u32_e32 v189, vcc, 0, v109, vcc
	global_load_dwordx4 v[200:203], v[188:189], off
	global_load_dwordx4 v[204:207], v[108:109], off offset:1024
	global_load_dwordx4 v[218:221], v[112:113], off offset:1024
	global_load_dwordx4 v[222:225], v[174:175], off offset:1024
	global_load_dwordx4 v[226:229], v[176:177], off offset:1024
	s_nop 0
	v_pk_fma_f32 v[194:195], v[106:107], v[194:195], v[198:199]
	s_mov_b32 s36, 0x3fd744fd
	s_waitcnt vmcnt(6)
	v_pk_add_f32 v[102:103], v[120:121], v[124:125]
	s_nop 0
	v_pk_fma_f32 v[90:91], v[90:91], s[36:37], v[102:103] op_sel_hi:[1,0,1]
	s_nop 0
	v_pk_add_f32 v[114:115], v[118:119], v[122:123]
	v_pk_fma_f32 v[114:115], v[126:127], s[36:37], v[114:115] op_sel_hi:[1,0,1]
	s_nop 0
	s_mov_b32 s19, 0x21200000
	s_waitcnt vmcnt(4)
	v_pk_add_f32 v[102:103], v[182:183], v[202:203]
	v_pk_add_f32 v[180:181], v[180:181], v[200:201]
	v_pk_add_f32 v[102:103], v[90:91], v[102:103]
	v_pk_add_f32 v[90:91], v[114:115], v[180:181]
	v_add_co_u32_e32 v114, vcc, s19, v88
	v_cvt_pkrtz_f16_f32 v118, v90, v91
	v_cvt_pkrtz_f16_f32 v119, v102, v103
	v_addc_co_u32_e32 v115, vcc, 0, v89, vcc
	global_store_dwordx2 v[114:115], v[118:119], off
	s_nop 0
	s_waitcnt vmcnt(3)
	v_pk_add_f32 v[206:207], v[206:207], v[220:221]
	v_pk_add_f32 v[204:205], v[204:205], v[218:219]
	v_pk_fma_f32 v[110:111], v[110:111], s[36:37], v[206:207] op_sel_hi:[1,0,1]
	v_pk_fma_f32 v[92:93], v[92:93], s[36:37], v[204:205] op_sel_hi:[1,0,1]
	s_waitcnt vmcnt(1)
	v_pk_add_f32 v[224:225], v[224:225], v[228:229]
	v_pk_add_f32 v[222:223], v[222:223], v[226:227]
	v_pk_add_f32 v[126:127], v[110:111], v[224:225]
	v_pk_add_f32 v[92:93], v[92:93], v[222:223]
	v_cvt_pkrtz_f16_f32 v111, v126, v127
	v_cvt_pkrtz_f16_f32 v110, v92, v93
	global_store_dwordx2 v[114:115], v[110:111], off offset:512
	global_load_dwordx4 v[118:121], v[108:109], off offset:2048
	global_load_dwordx4 v[122:125], v[112:113], off offset:2048
	global_load_dwordx4 v[178:181], v[174:175], off offset:2048
	global_load_dwordx4 v[188:191], v[176:177], off offset:2048
	global_load_dwordx4 v[196:199], v[108:109], off offset:3072
	global_load_dwordx4 v[200:203], v[112:113], off offset:3072
	global_load_dwordx4 v[204:207], v[174:175], off offset:3072
	global_load_dwordx4 v[104:107], v[176:177], off offset:3072
	s_waitcnt vmcnt(6)
	v_pk_add_f32 v[110:111], v[120:121], v[124:125]
	v_pk_add_f32 v[118:119], v[118:119], v[122:123]
	v_pk_fma_f32 v[110:111], v[186:187], s[36:37], v[110:111] op_sel_hi:[1,0,1]
	v_pk_fma_f32 v[122:123], v[184:185], s[36:37], v[118:119] op_sel_hi:[1,0,1]
	s_waitcnt vmcnt(4)
	v_pk_add_f32 v[180:181], v[180:181], v[190:191]
	v_pk_add_f32 v[188:189], v[178:179], v[188:189]
	v_pk_add_f32 v[94:95], v[110:111], v[180:181]
	v_pk_add_f32 v[96:97], v[122:123], v[188:189]
	v_cvt_pkrtz_f16_f32 v111, v94, v95
	v_cvt_pkrtz_f16_f32 v110, v96, v97
	global_store_dwordx2 v[114:115], v[110:111], off offset:1024
	s_nop 0
	s_waitcnt vmcnt(3)
	v_pk_add_f32 v[198:199], v[198:199], v[202:203]
	v_pk_add_f32 v[196:197], v[196:197], v[200:201]
	v_pk_fma_f32 v[198:199], v[194:195], s[36:37], v[198:199] op_sel_hi:[1,0,1]
	v_pk_fma_f32 v[196:197], v[192:193], s[36:37], v[196:197] op_sel_hi:[1,0,1]
	s_nop 0
	s_waitcnt vmcnt(1)
	v_pk_add_f32 v[206:207], v[206:207], v[106:107]
	v_pk_add_f32 v[104:105], v[204:205], v[104:105]
	v_pk_add_f32 v[98:99], v[198:199], v[206:207]
	v_pk_add_f32 v[100:101], v[196:197], v[104:105]
	v_cvt_pkrtz_f16_f32 v105, v98, v99
	v_cvt_pkrtz_f16_f32 v104, v100, v101
	global_store_dwordx2 v[114:115], v[104:105], off offset:1536
	v_mov_b32_e32 v106, v91
	v_mov_b32_e32 v107, v102
	v_mov_b32_e32 v91, v103
	v_mov_b32_e32 v102, v93
	v_mov_b32_e32 v103, v126
	v_mov_b32_e32 v93, v127
	v_mov_b32_e32 v104, v101
	v_mov_b32_e32 v108, v99

; DI float hlo(unsigned u) { return (float)__builtin_bit_cast(f16x2_t, u).x; }
; DI float hhi(unsigned u) { return (float)__builtin_bit_cast(f16x2_t, u).y; }
; DI void lnmod_phase(const Args& A, LAS unsigned char* lds, int tid, int bid, int G, bool init, int l_norm, int i_norm, int l_mod, int i_mod, bool want_dt, int nrows, bool ctx_partial, const float* gprev, const float* bprev) {
;     ...
;         for (int j = 0; j < 4; ++j) v[j] = init ? fn[j] : (f32x4){hlo(un[j].x), hhi(un[j].x), hlo(un[j].y), hhi(un[j].y)};
;         { const int rown = row + G * 8;
;           if (rown < nrows) {
;               if (init) { const float* xin = rown < M_LAT ? A.in[I_X] + (size_t)rown * DM : A.in[I_CTX] + (size_t)(rown - M_LAT) * DM;
; #pragma unroll
;                   for (int j = 0; j < 4; ++j) fn[j] = *(const f32x4*)(xin + 256 * j + 4 * lane); }
;               else {
; #pragma unroll
;                   for (int j = 0; j < 4; ++j) un[j] = *(const u32x2*)(X16 + (size_t)rown * DM + 256 * j + 4 * lane); } } }
;         f32x2* STAT = (f32x2*)(A.ws + WS_STAT);
;         if (ctx_partial && row >= M_LAT) {
.LBB0_231:
	s_or_b64 exec, exec, s[4:5]
	v_cvt_f32_f16_sdwa v108, v66 dst_sel:DWORD dst_unused:UNUSED_PAD src0_sel:WORD_1
	v_cvt_f32_f16_e32 v64, v66
	v_cvt_f32_f16_sdwa v65, v67 dst_sel:DWORD dst_unused:UNUSED_PAD src0_sel:WORD_1
	v_cvt_f32_f16_e32 v109, v67
	v_cvt_f32_f16_sdwa v66, v72 dst_sel:DWORD dst_unused:UNUSED_PAD src0_sel:WORD_1
	v_cvt_f32_f16_e32 v68, v72
	v_cvt_f32_f16_sdwa v69, v73 dst_sel:DWORD dst_unused:UNUSED_PAD src0_sel:WORD_1
	v_cvt_f32_f16_e32 v67, v73
	v_cvt_f32_f16_sdwa v73, v70 dst_sel:DWORD dst_unused:UNUSED_PAD src0_sel:WORD_1
	v_cvt_f32_f16_e32 v72, v70
	v_cvt_f32_f16_sdwa v75, v71 dst_sel:DWORD dst_unused:UNUSED_PAD src0_sel:WORD_1
	v_cvt_f32_f16_e32 v74, v71
	v_cvt_f32_f16_sdwa v70, v76 dst_sel:DWORD dst_unused:UNUSED_PAD src0_sel:WORD_1
	v_cvt_f32_f16_e32 v76, v76
	v_cvt_f32_f16_sdwa v106, v77 dst_sel:DWORD dst_unused:UNUSED_PAD src0_sel:WORD_1
	v_cvt_f32_f16_e32 v78, v77
	s_movk_i32 s4, 0x7fff
	v_cmp_lt_i32_e32 vcc, s4, v118
	v_readlane_b32 s4, v253, 37
	v_readlane_b32 s40, v253, 23
	v_readlane_b32 s5, v253, 38
	v_readlane_b32 s42, v253, 25
	v_readlane_b32 s43, v253, 26
	s_and_b64 s[36:37], s[4:5], vcc
	v_readlane_b32 s41, v253, 24
	v_lshl_add_u64 v[104:105], s[42:43], 0, v[82:83]
	s_and_saveexec_b64 s[4:5], s[36:37]
	s_cbranch_execz .LBB0_233
; DI unsigned pkh2(float lo, float hi) { return __builtin_bit_cast(unsigned, __builtin_amdgcn_cvt_pkrtz(lo, hi)); }
; DI void lnmod_phase(const Args& A, LAS unsigned char* lds, int tid, int bid, int G, bool init, int l_norm, int i_norm, int l_mod, int i_mod, bool want_dt, int nrows, bool ctx_partial, const float* gprev, const float* bprev) {
;     ...
;         if (ctx_partial && row >= M_LAT) {
;             { const f32x2 st = STAT[row];
; #pragma unroll
;               for (int j = 0; j < 4; ++j) v[j] = (v[j] - st.x) * st.y * *(const f32x4*)(gprev + 256 * j + 4 * lane) + *(const f32x4*)(bprev + 256 * j + 4 * lane); }
;             const float* t0 = (const float*)(A.ws + WS_T) + (size_t)(row - M_LAT) * DM; const float* t1 = t0 + (size_t)M_CTX * DM; const float* t2 = t1 + (size_t)M_CTX * DM; const float* t3 = t2 + (size_t)M_CTX * DM;
; #pragma unroll
;             for (int j = 0; j < 4; ++j) { v[j] = v[j] * ALPHA + (*(const f32x4*)(t0 + 256 * j + 4 * lane) + *(const f32x4*)(t1 + 256 * j + 4 * lane)) + (*(const f32x4*)(t2 + 256 * j + 4 * lane) + *(const f32x4*)(t3 + 256 * j + 4 * lane)); u32x2 w_; w_.x = pkh2(v[j].x, v[j].y); w_.y = pkh2(v[j].z, v[j].w); *(u32x2*)(xout + 256 * j + 4 * lane) = w_; }
;         }
	v_readlane_b32 s38, v253, 25
	v_readlane_b32 s39, v253, 26
	v_add_u32_e32 v146, 0xffff8000, v118
	s_nop 1
	v_lshl_add_u64 v[110:111], s[38:39], 0, v[92:93]
	global_load_dwordx2 v[120:121], v[110:111], off
	v_readlane_b32 s36, v251, 61
	v_readlane_b32 s37, v251, 62
	s_mov_b32 s7, 0x800000
	global_load_dwordx4 v[130:133], v[86:87], off
	global_load_dwordx4 v[112:115], v[88:89], off
	global_load_dwordx4 v[134:137], v[86:87], off offset:1024
	global_load_dwordx4 v[138:141], v[88:89], off offset:1024
	global_load_dwordx4 v[154:157], v[86:87], off offset:2048
	global_load_dwordx4 v[160:163], v[88:89], off offset:2048
	global_load_dwordx4 v[164:167], v[86:87], off offset:3072
	global_load_dwordx4 v[168:171], v[88:89], off offset:3072
	s_waitcnt vmcnt(8)
	v_sub_f32_e32 v111, v108, v120
	v_sub_f32_e32 v110, v64, v120
	v_sub_f32_e32 v64, v109, v120
	v_pk_mul_f32 v[122:123], v[120:121], v[110:111] op_sel:[1,0]
	v_sub_f32_e32 v65, v65, v120
	v_pk_mul_f32 v[64:65], v[120:121], v[64:65] op_sel:[1,0]
	v_sub_f32_e32 v69, v69, v120
	s_waitcnt vmcnt(6)
	v_pk_fma_f32 v[114:115], v[132:133], v[64:65], v[114:115]
	v_sub_f32_e32 v65, v66, v120
	v_sub_f32_e32 v64, v68, v120
	v_sub_f32_e32 v68, v67, v120
	v_pk_fma_f32 v[128:129], v[130:131], v[122:123], v[112:113]
	v_pk_mul_f32 v[112:113], v[120:121], v[68:69] op_sel:[1,0]
	v_pk_mul_f32 v[68:69], v[120:121], v[64:65] op_sel:[1,0]
	s_waitcnt vmcnt(4)
	v_pk_fma_f32 v[68:69], v[68:69], v[134:135], v[138:139]
	v_pk_fma_f32 v[108:109], v[112:113], v[136:137], v[140:141]
	v_sub_f32_e32 v65, v73, v120
	v_sub_f32_e32 v64, v72, v120
	v_sub_f32_e32 v67, v75, v120
	v_sub_f32_e32 v66, v74, v120
	v_pk_mul_f32 v[110:111], v[120:121], v[66:67] op_sel:[1,0]
	v_pk_mul_f32 v[112:113], v[120:121], v[64:65] op_sel:[1,0]
	s_waitcnt vmcnt(2)
	v_pk_fma_f32 v[160:161], v[112:113], v[154:155], v[160:161]
	v_pk_fma_f32 v[162:163], v[110:111], v[156:157], v[162:163]
	v_sub_f32_e32 v64, v76, v120
	v_sub_f32_e32 v66, v78, v120
	v_sub_f32_e32 v65, v70, v120
	v_sub_f32_e32 v67, v106, v120
	v_pk_mul_f32 v[64:65], v[120:121], v[64:65] op_sel:[1,0]
	v_pk_mul_f32 v[70:71], v[120:121], v[66:67] op_sel:[1,0]
	s_waitcnt vmcnt(0)
	v_pk_fma_f32 v[66:67], v[64:65], v[164:165], v[168:169]
	v_lshlrev_b64 v[64:65], 12, v[146:147]
	v_lshl_add_u64 v[64:65], s[36:37], 0, v[64:65]
	v_lshlrev_b32_e32 v146, 2, v84
	v_lshl_add_u64 v[110:111], v[64:65], 0, v[146:147]
	v_add_co_u32_e32 v130, vcc, s7, v110
	global_load_dwordx4 v[120:123], v[110:111], off
	s_nop 1
	v_addc_co_u32_e32 v131, vcc, 0, v111, vcc
	global_load_dwordx4 v[124:127], v[130:131], off
	s_mov_b64 s[36:37], 0x800000
	v_lshl_add_u64 v[132:133], v[110:111], 0, s[36:37]
	s_mov_b64 s[36:37], 0x1000000
	v_lshl_add_u64 v[76:77], v[110:111], 0, s[36:37]
	s_mov_b64 s[36:37], 0x1800000
	v_lshl_add_u64 v[134:135], v[110:111], 0, s[36:37]
	s_mov_b32 s7, 0x1000000
	v_add_co_u32_e32 v136, vcc, s7, v110
	s_mov_b32 s7, 0x1800000
	s_nop 1
	v_addc_co_u32_e32 v137, vcc, 0, v111, vcc
	global_load_dwordx4 v[138:141], v[136:137], off
	v_add_co_u32_e32 v142, vcc, s7, v110
	s_nop 1
	v_addc_co_u32_e32 v143, vcc, 0, v111, vcc
	global_load_dwordx4 v[154:157], v[142:143], off
	global_load_dwordx4 v[172:175], v[110:111], off offset:1024
	global_load_dwordx4 v[176:179], v[132:133], off offset:1024
	global_load_dwordx4 v[180:183], v[76:77], off offset:1024
	global_load_dwordx4 v[184:187], v[134:135], off offset:1024
	global_load_dwordx4 v[188:191], v[110:111], off offset:2048
	global_load_dwordx4 v[192:195], v[132:133], off offset:2048
	global_load_dwordx4 v[196:199], v[76:77], off offset:2048
	global_load_dwordx4 v[200:203], v[134:135], off offset:2048
	global_load_dwordx4 v[204:207], v[110:111], off offset:3072
	global_load_dwordx4 v[218:221], v[132:133], off offset:3072
	global_load_dwordx4 v[222:225], v[76:77], off offset:3072
	global_load_dwordx4 v[226:229], v[134:135], off offset:3072
	s_nop 0
	v_pk_fma_f32 v[70:71], v[70:71], v[166:167], v[170:171]
	s_mov_b32 s36, 0x3fd744fd
	s_waitcnt vmcnt(14)
	v_pk_add_f32 v[64:65], v[122:123], v[126:127]
	v_pk_add_f32 v[106:107], v[120:121], v[124:125]
	v_pk_fma_f32 v[64:65], v[114:115], s[36:37], v[64:65] op_sel_hi:[1,0,1]
	v_pk_fma_f32 v[114:115], v[128:129], s[36:37], v[106:107] op_sel_hi:[1,0,1]
	s_nop 0
	s_mov_b32 s7, 0x21200000
	s_nop 0
	s_waitcnt vmcnt(12)
	v_pk_add_f32 v[106:107], v[140:141], v[156:157]
	v_pk_add_f32 v[138:139], v[138:139], v[154:155]
	v_pk_add_f32 v[106:107], v[64:65], v[106:107]
	v_pk_add_f32 v[64:65], v[114:115], v[138:139]
	v_add_co_u32_e32 v114, vcc, s7, v104
	v_cvt_pkrtz_f16_f32 v120, v64, v65
	v_cvt_pkrtz_f16_f32 v121, v106, v107
	v_addc_co_u32_e32 v115, vcc, 0, v105, vcc
	global_store_dwordx2 v[114:115], v[120:121], off
	s_nop 0
	s_waitcnt vmcnt(11)
	v_pk_add_f32 v[174:175], v[174:175], v[178:179]
	v_pk_add_f32 v[172:173], v[172:173], v[176:177]
	v_pk_fma_f32 v[108:109], v[108:109], s[36:37], v[174:175] op_sel_hi:[1,0,1]
	v_pk_fma_f32 v[68:69], v[68:69], s[36:37], v[172:173] op_sel_hi:[1,0,1]
	s_waitcnt vmcnt(9)
	v_pk_add_f32 v[182:183], v[182:183], v[186:187]
	v_pk_add_f32 v[180:181], v[180:181], v[184:185]
	v_pk_add_f32 v[128:129], v[108:109], v[182:183]
	v_pk_add_f32 v[68:69], v[68:69], v[180:181]
	v_cvt_pkrtz_f16_f32 v109, v128, v129
	v_cvt_pkrtz_f16_f32 v108, v68, v69
	global_store_dwordx2 v[114:115], v[108:109], off offset:512
	s_waitcnt vmcnt(8)
	v_pk_add_f32 v[108:109], v[190:191], v[194:195]
	v_pk_add_f32 v[188:189], v[188:189], v[192:193]
	v_pk_fma_f32 v[108:109], v[162:163], s[36:37], v[108:109] op_sel_hi:[1,0,1]
	v_pk_fma_f32 v[124:125], v[160:161], s[36:37], v[188:189] op_sel_hi:[1,0,1]
	s_waitcnt vmcnt(6)
	v_pk_add_f32 v[198:199], v[198:199], v[202:203]
	v_pk_add_f32 v[196:197], v[196:197], v[200:201]
	v_pk_add_f32 v[198:199], v[108:109], v[198:199]
	v_pk_add_f32 v[196:197], v[124:125], v[196:197]
	v_cvt_pkrtz_f16_f32 v109, v198, v199
	v_cvt_pkrtz_f16_f32 v108, v196, v197
	global_store_dwordx2 v[114:115], v[108:109], off offset:1024
	s_nop 0
	s_waitcnt vmcnt(5)
	v_pk_add_f32 v[206:207], v[206:207], v[220:221]
	v_pk_add_f32 v[204:205], v[204:205], v[218:219]
	v_pk_fma_f32 v[70:71], v[70:71], s[36:37], v[206:207] op_sel_hi:[1,0,1]
	v_pk_fma_f32 v[66:67], v[66:67], s[36:37], v[204:205] op_sel_hi:[1,0,1]
	s_nop 0
	s_waitcnt vmcnt(3)
	v_pk_add_f32 v[228:229], v[224:225], v[228:229]
	v_pk_add_f32 v[226:227], v[222:223], v[226:227]
	v_pk_add_f32 v[228:229], v[70:71], v[228:229]
	v_pk_add_f32 v[226:227], v[66:67], v[226:227]
	v_cvt_pkrtz_f16_f32 v67, v228, v229
	v_cvt_pkrtz_f16_f32 v66, v226, v227
	global_store_dwordx2 v[114:115], v[66:67], off offset:1536
	v_mov_b32_e32 v108, v65
	v_mov_b32_e32 v109, v106
	v_mov_b32_e32 v65, v107
	v_mov_b32_e32 v66, v69
	v_mov_b32_e32 v67, v128
	v_mov_b32_e32 v69, v129
	v_mov_b32_e32 v70, v227
	v_mov_b32_e32 v106, v229
	v_mov_b32_e32 v72, v196
	v_mov_b32_e32 v73, v197
	v_mov_b32_e32 v74, v198
	v_mov_b32_e32 v75, v199
	v_mov_b32_e32 v76, v226
	v_mov_b32_e32 v78, v228

; #define LAS __attribute__((address_space(3)))
; DI unsigned pk2(float lo, float hi) { f32x2 v = {lo, hi}; bf16x2_t b = __builtin_convertvector(v, bf16x2_t); return __builtin_bit_cast(unsigned, b); }
; DI void transpose_item_wide(const float* W, int ldw, int K, int src0, bf16* WT, int n0, int k0, LAS float* scr, int lane) {
;     const int c4 = lane & 7, kr = lane >> 3;
; #pragma unroll
;     for (int i = 0; i < 8; ++i) { const int kk = kr + 8 * i; const f32x4 v = *(const f32x4*)(W + (size_t)(k0 + kk) * ldw + src0 + 4 * c4);
;         LAS float* d = scr + kk * 33 + 4 * c4; d[0] = v.x; d[1] = v.y; d[2] = v.z; d[3] = v.w; }
;     asm volatile("s_waitcnt lgkmcnt(0)" ::: "memory");
;     const int c = lane & 7;
; #pragma unroll
;     for (int j = 0; j < 4; ++j) {
;         const int n = (lane >> 3) + 8 * j; const LAS float* sp = scr + (8 * c) * 33 + n;
;         u32x4 o; o.x = pk2(sp[0 * 33], sp[1 * 33]); o.y = pk2(sp[2 * 33], sp[3 * 33]); o.z = pk2(sp[4 * 33], sp[5 * 33]); o.w = pk2(sp[6 * 33], sp[7 * 33]);
;         *(u32x4*)(WT + (size_t)(n0 + n) * K + k0 + 8 * c) = o;
;     }
;     asm volatile("s_waitcnt lgkmcnt(0)" ::: "memory");
; }
; DI void convw_phase(const Args& A, int l, LAS unsigned char* lds, int tid, int bid, int G) {
;     ...
;         r -= I_IN;
;         { const int kb = r / 32, nb = r % 32;
;           transpose_item_wide(A.in[I_WOUT] + (size_t)l * DM * DM, DM, DM, nb * 32, wout, nb * 32, kb * 64, scr, lane); }
.LBB0_246:
	s_movk_i32 s2, 0x15ff
	v_cmp_lt_i32_e32 vcc, s2, v80
	s_and_saveexec_b64 s[2:3], vcc
	s_xor_b64 s[8:9], exec, s[2:3]
	s_cbranch_execz .LBB0_268
	s_movk_i32 s2, 0x20ff
	v_cmp_lt_u32_e32 vcc, s2, v80
	s_and_saveexec_b64 s[2:3], vcc
	s_xor_b64 s[2:3], exec, s[2:3]
	s_cbranch_execz .LBB0_265
	s_movk_i32 s14, 0x27ff
	v_cmp_lt_u32_e32 vcc, s14, v80
	s_and_saveexec_b64 s[14:15], vcc
	s_xor_b64 s[14:15], exec, s[14:15]
	s_cbranch_execz .LBB0_250
	v_lshlrev_b32_e32 v0, 5, v80
	v_and_b32_e32 v2, 0x3e0, v0
	v_lshlrev_b32_e32 v0, 1, v80
	v_and_b32_e32 v0, 0x7fffffc0, v0
	v_add_u32_e32 v0, 0xffffb000, v0
	v_lshlrev_b32_e32 v146, 2, v2
	v_lshl_add_u64 v[18:19], v[16:17], 0, v[146:147]
	v_or_b32_e32 v146, v0, v7
	v_lshlrev_b64 v[32:33], 12, v[146:147]
	v_lshl_add_u64 v[32:33], v[18:19], 0, v[32:33]
	global_load_dwordx4 v[96:99], v[32:33], off
	v_or_b32_e32 v146, v0, v20
	v_lshlrev_b64 v[128:129], 12, v[146:147]
	v_lshl_add_u64 v[130:131], v[18:19], 0, v[128:129]
	global_load_dwordx4 v[100:103], v[130:131], off
	v_or_b32_e32 v146, v0, v21
	v_lshlrev_b64 v[132:133], 12, v[146:147]
	v_lshl_add_u64 v[134:135], v[18:19], 0, v[132:133]
	global_load_dwordx4 v[104:107], v[134:135], off
	v_or_b32_e32 v146, v0, v22
	v_lshlrev_b64 v[136:137], 12, v[146:147]
	v_lshl_add_u64 v[138:139], v[18:19], 0, v[136:137]
	global_load_dwordx4 v[108:111], v[138:139], off
	v_or_b32_e32 v146, v0, v23
	v_lshlrev_b64 v[140:141], 12, v[146:147]
	v_lshl_add_u64 v[142:143], v[18:19], 0, v[140:141]
	global_load_dwordx4 v[112:115], v[142:143], off
	v_or_b32_e32 v146, v0, v24
	v_lshlrev_b64 v[160:161], 12, v[146:147]
	v_lshl_add_u64 v[162:163], v[18:19], 0, v[160:161]
	global_load_dwordx4 v[116:119], v[162:163], off
	v_or_b32_e32 v146, v0, v25
	v_lshlrev_b64 v[164:165], 12, v[146:147]
	v_lshl_add_u64 v[166:167], v[18:19], 0, v[164:165]
	global_load_dwordx4 v[120:123], v[166:167], off
	v_or_b32_e32 v146, v0, v26
	v_lshlrev_b64 v[168:169], 12, v[146:147]
	v_lshl_add_u64 v[170:171], v[18:19], 0, v[168:169]
	global_load_dwordx4 v[124:127], v[170:171], off
	v_add_u32_e32 v1, v11, v13
	v_add_u32_e32 v3, 0x420, v1
	s_waitcnt vmcnt(7)
	ds_write2_b32 v1, v96, v97 offset1:1
	ds_write2_b32 v1, v98, v99 offset0:2 offset1:3
	s_waitcnt vmcnt(6)
	ds_write2_b32 v3, v100, v101 offset1:1
	v_add_u32_e32 v3, 0x428, v1
	ds_write2_b32 v3, v102, v103 offset1:1
	v_add_u32_e32 v3, 0x840, v1
	s_waitcnt vmcnt(5)
	ds_write2_b32 v3, v104, v105 offset1:1
	v_add_u32_e32 v3, 0x848, v1
	ds_write2_b32 v3, v106, v107 offset1:1
	v_add_u32_e32 v3, 0xc60, v1
	s_waitcnt vmcnt(4)
	ds_write2_b32 v3, v108, v109 offset1:1
	v_add_u32_e32 v3, 0xc68, v1
	ds_write2_b32 v3, v110, v111 offset1:1
	v_add_u32_e32 v3, 0x1080, v1
	s_waitcnt vmcnt(3)
	ds_write2_b32 v3, v112, v113 offset1:1
	v_add_u32_e32 v3, 0x1088, v1
	ds_write2_b32 v3, v114, v115 offset1:1
	v_add_u32_e32 v3, 0x14a0, v1
	s_waitcnt vmcnt(2)
	ds_write2_b32 v3, v116, v117 offset1:1
	v_add_u32_e32 v3, 0x14a8, v1
	ds_write2_b32 v3, v118, v119 offset1:1
	v_add_u32_e32 v3, 0x18c0, v1
	s_waitcnt vmcnt(1)
	ds_write2_b32 v3, v120, v121 offset1:1
	v_add_u32_e32 v3, 0x18c8, v1
	ds_write2_b32 v3, v122, v123 offset1:1
	v_add_u32_e32 v3, 0x1ce0, v1
	v_add_u32_e32 v1, 0x1ce8, v1
	s_waitcnt vmcnt(0)
	ds_write2_b32 v3, v124, v125 offset1:1
	ds_write2_b32 v1, v126, v127 offset1:1
	s_waitcnt lgkmcnt(0)
	ds_read2_b32 v[18:19], v27 offset0:33 offset1:41
	ds_read2_b32 v[36:37], v27 offset1:8
	ds_read2_b32 v[38:39], v27 offset0:66 offset1:74
	ds_read2_b32 v[40:41], v27 offset0:99 offset1:107
	ds_read2_b32 v[42:43], v27 offset0:132 offset1:140
	ds_read2_b32 v[44:45], v27 offset0:165 offset1:173
	ds_read2_b32 v[46:47], v27 offset0:198 offset1:206
	ds_read2_b32 v[48:49], v27 offset0:231 offset1:239
	v_mov_b32_e32 v1, v147
	v_or_b32_e32 v3, v2, v7
	v_lshl_add_u64 v[0:1], v[0:1], 1, v[8:9]
	v_lshlrev_b32_e32 v146, 11, v3
	v_or_b32_e32 v3, v2, v20
	s_waitcnt lgkmcnt(6)
	v_cvt_pk_bf16_f32 v32, v36, v18
	s_waitcnt lgkmcnt(4)
	v_cvt_pk_bf16_f32 v33, v38, v40
	s_waitcnt lgkmcnt(2)
	v_cvt_pk_bf16_f32 v34, v42, v44
	s_waitcnt lgkmcnt(0)
	v_cvt_pk_bf16_f32 v35, v46, v48
	v_lshl_add_u64 v[50:51], v[0:1], 0, v[146:147]
	v_lshlrev_b32_e32 v146, 11, v3
	global_store_dwordx4 v[50:51], v[32:35], off
	v_or_b32_e32 v3, v2, v21
	v_or_b32_e32 v2, v2, v22
	v_cvt_pk_bf16_f32 v32, v37, v19
	v_cvt_pk_bf16_f32 v33, v39, v41
	v_cvt_pk_bf16_f32 v34, v43, v45
	v_cvt_pk_bf16_f32 v35, v47, v49
	v_lshl_add_u64 v[18:19], v[0:1], 0, v[146:147]
	global_store_dwordx4 v[18:19], v[32:35], off
	ds_read2_b32 v[18:19], v27 offset0:49 offset1:57
	ds_read2_b32 v[36:37], v27 offset0:16 offset1:24
	ds_read2_b32 v[38:39], v27 offset0:82 offset1:90
	ds_read2_b32 v[40:41], v27 offset0:115 offset1:123
	ds_read2_b32 v[42:43], v27 offset0:148 offset1:156
	ds_read2_b32 v[44:45], v27 offset0:181 offset1:189
	ds_read2_b32 v[46:47], v27 offset0:214 offset1:222
	ds_read2_b32 v[48:49], v27 offset0:247 offset1:255
	v_lshlrev_b32_e32 v146, 11, v3
	s_waitcnt lgkmcnt(6)
	v_cvt_pk_bf16_f32 v32, v36, v18
	s_waitcnt lgkmcnt(4)
	v_cvt_pk_bf16_f32 v33, v38, v40
	s_waitcnt lgkmcnt(2)
	v_cvt_pk_bf16_f32 v34, v42, v44
	s_waitcnt lgkmcnt(0)
	v_cvt_pk_bf16_f32 v35, v46, v48
	v_lshl_add_u64 v[50:51], v[0:1], 0, v[146:147]
	v_lshlrev_b32_e32 v146, 11, v2
	global_store_dwordx4 v[50:51], v[32:35], off
	v_lshl_add_u64 v[0:1], v[0:1], 0, v[146:147]
	s_nop 0
	v_cvt_pk_bf16_f32 v32, v37, v19
	v_cvt_pk_bf16_f32 v33, v39, v41
	v_cvt_pk_bf16_f32 v34, v43, v45
	v_cvt_pk_bf16_f32 v35, v47, v49
	global_store_dwordx4 v[0:1], v[32:35], off
	s_waitcnt lgkmcnt(0)

; #define LAS __attribute__((address_space(3)))
; DI unsigned pk2(float lo, float hi) { f32x2 v = {lo, hi}; bf16x2_t b = __builtin_convertvector(v, bf16x2_t); return __builtin_bit_cast(unsigned, b); }
; DI void transpose_item_wide(const float* W, int ldw, int K, int src0, bf16* WT, int n0, int k0, LAS float* scr, int lane) {
;     const int c4 = lane & 7, kr = lane >> 3;
; #pragma unroll
;     for (int i = 0; i < 8; ++i) { const int kk = kr + 8 * i; const f32x4 v = *(const f32x4*)(W + (size_t)(k0 + kk) * ldw + src0 + 4 * c4);
;         LAS float* d = scr + kk * 33 + 4 * c4; d[0] = v.x; d[1] = v.y; d[2] = v.z; d[3] = v.w; }
;     asm volatile("s_waitcnt lgkmcnt(0)" ::: "memory");
;     const int c = lane & 7;
; #pragma unroll
;     for (int j = 0; j < 4; ++j) {
;         const int n = (lane >> 3) + 8 * j; const LAS float* sp = scr + (8 * c) * 33 + n;
;         u32x4 o; o.x = pk2(sp[0 * 33], sp[1 * 33]); o.y = pk2(sp[2 * 33], sp[3 * 33]); o.z = pk2(sp[4 * 33], sp[5 * 33]); o.w = pk2(sp[6 * 33], sp[7 * 33]);
;         *(u32x4*)(WT + (size_t)(n0 + n) * K + k0 + 8 * c) = o;
;     }
;     asm volatile("s_waitcnt lgkmcnt(0)" ::: "memory");
; }
; DI void convw_phase(const Args& A, int l, LAS unsigned char* lds, int tid, int bid, int G) {
;     ...
;         if (r < I_DN) {
;             const int f = r / ((DFF / 64) * 32); r -= f * (DFF / 64) * 32;
;             const int kb = r / 32, nb = r % 32;
;             transpose_item_wide(A.in[I_WD] + (size_t)(l * 2 + f) * DFF * DM, DM, DFF, nb * 32, wdn + (size_t)f * DM * DFF, nb * 32, kb * 64, scr, lane);
;             continue;
;         }
.LBB0_265:
	s_andn2_saveexec_b64 s[2:3], s[2:3]
	s_cbranch_execz .LBB0_267
	v_add_u32_e32 v0, 0xffffea00, v80
	s_movk_i32 s14, 0x57f
	v_cmp_lt_u32_e32 vcc, s14, v0
	v_readlane_b32 s36, v252, 10
	v_readlane_b32 s37, v252, 11
	v_cndmask_b32_e32 v2, 0, v212, vcc
	v_add_u32_e32 v0, v2, v0
	v_ashrrev_i16_e32 v2, 15, v0
	v_lshrrev_b16_e32 v2, 11, v2
	v_add_u16_e32 v2, v0, v2
	v_cndmask_b32_e64 v1, 0, 1, vcc
	v_ashrrev_i16_e32 v18, 5, v2
	v_and_b32_e32 v2, 0xffffffe0, v2
	v_sub_u16_e32 v2, v0, v2
	v_or_b32_e32 v3, s23, v1
	v_mov_b64_e32 v[0:1], s[36:37]
	s_mov_b32 s14, 0xb00000
	v_mad_i64_i32 v[32:33], s[14:15], v3, s14, v[0:1]
	v_lshlrev_b32_sdwa v0, v213, sext(v2) dst_sel:DWORD dst_unused:UNUSED_PAD src0_sel:DWORD src1_sel:WORD_0
	v_readlane_b32 s14, v252, 1
	v_cndmask_b32_e32 v146, 0, v214, vcc
	v_readlane_b32 s15, v252, 2
	v_ashrrev_i32_e32 v1, 31, v0
	v_lshlrev_b32_sdwa v18, v211, sext(v18) dst_sel:DWORD dst_unused:UNUSED_PAD src0_sel:DWORD src1_sel:WORD_0
	v_lshl_add_u64 v[2:3], s[14:15], 0, v[146:147]
	v_lshl_add_u64 v[32:33], v[0:1], 2, v[32:33]
	v_lshlrev_b32_e32 v146, 2, v4
	v_lshl_add_u64 v[36:37], v[32:33], 0, v[146:147]
	v_or_b32_e32 v32, v18, v7
	v_ashrrev_i32_e32 v33, 31, v32
	v_lshlrev_b64 v[32:33], 12, v[32:33]
	v_lshl_add_u64 v[32:33], v[36:37], 0, v[32:33]
	global_load_dwordx4 v[96:99], v[32:33], off
	v_or_b32_e32 v128, v18, v20
	v_ashrrev_i32_e32 v129, 31, v128
	v_lshlrev_b64 v[130:131], 12, v[128:129]
	v_lshl_add_u64 v[132:133], v[36:37], 0, v[130:131]
	global_load_dwordx4 v[100:103], v[132:133], off
	v_or_b32_e32 v134, v18, v21
	v_ashrrev_i32_e32 v135, 31, v134
	v_lshlrev_b64 v[136:137], 12, v[134:135]
	v_lshl_add_u64 v[138:139], v[36:37], 0, v[136:137]
	global_load_dwordx4 v[104:107], v[138:139], off
	v_or_b32_e32 v140, v18, v22
	v_ashrrev_i32_e32 v141, 31, v140
	v_lshlrev_b64 v[142:143], 12, v[140:141]
	v_lshl_add_u64 v[160:161], v[36:37], 0, v[142:143]
	global_load_dwordx4 v[108:111], v[160:161], off
	v_or_b32_e32 v162, v18, v23
	v_ashrrev_i32_e32 v163, 31, v162
	v_lshlrev_b64 v[164:165], 12, v[162:163]
	v_lshl_add_u64 v[166:167], v[36:37], 0, v[164:165]
	global_load_dwordx4 v[112:115], v[166:167], off
	v_or_b32_e32 v168, v18, v24
	v_ashrrev_i32_e32 v169, 31, v168
	v_lshlrev_b64 v[170:171], 12, v[168:169]
	v_lshl_add_u64 v[172:173], v[36:37], 0, v[170:171]
	global_load_dwordx4 v[116:119], v[172:173], off
	v_or_b32_e32 v174, v18, v25
	v_ashrrev_i32_e32 v175, 31, v174
	v_lshlrev_b64 v[176:177], 12, v[174:175]
	v_lshl_add_u64 v[178:179], v[36:37], 0, v[176:177]
	global_load_dwordx4 v[120:123], v[178:179], off
	v_or_b32_e32 v180, v18, v26
	v_ashrrev_i32_e32 v181, 31, v180
	v_lshlrev_b64 v[182:183], 12, v[180:181]
	v_lshl_add_u64 v[184:185], v[36:37], 0, v[182:183]
	global_load_dwordx4 v[124:127], v[184:185], off
	v_add_u32_e32 v1, v11, v13
	v_add_u32_e32 v19, 0x420, v1
	v_lshlrev_b32_e32 v146, 1, v6
	v_readlane_b32 s38, v252, 12
	v_readlane_b32 s39, v252, 13
	v_readlane_b32 s40, v252, 14
	v_readlane_b32 s41, v252, 15
	v_readlane_b32 s42, v252, 16
	v_readlane_b32 s43, v252, 17
	v_readlane_b32 s44, v252, 18
	v_readlane_b32 s45, v252, 19
	v_readlane_b32 s46, v252, 20
	v_readlane_b32 s47, v252, 21
	v_readlane_b32 s48, v252, 22
	v_readlane_b32 s49, v252, 23
	v_readlane_b32 s50, v252, 24
	v_readlane_b32 s51, v252, 25
	s_waitcnt vmcnt(7)
	ds_write2_b32 v1, v96, v97 offset1:1
	ds_write2_b32 v1, v98, v99 offset0:2 offset1:3
	s_waitcnt vmcnt(6)
	ds_write2_b32 v19, v100, v101 offset1:1
	v_add_u32_e32 v19, 0x428, v1
	ds_write2_b32 v19, v102, v103 offset1:1
	v_add_u32_e32 v19, 0x840, v1
	s_waitcnt vmcnt(5)
	ds_write2_b32 v19, v104, v105 offset1:1
	v_add_u32_e32 v19, 0x848, v1
	ds_write2_b32 v19, v106, v107 offset1:1
	v_add_u32_e32 v19, 0xc60, v1
	s_waitcnt vmcnt(4)
	ds_write2_b32 v19, v108, v109 offset1:1
	v_add_u32_e32 v19, 0xc68, v1
	ds_write2_b32 v19, v110, v111 offset1:1
	v_add_u32_e32 v19, 0x1080, v1
	s_waitcnt vmcnt(3)
	ds_write2_b32 v19, v112, v113 offset1:1
	v_add_u32_e32 v19, 0x1088, v1
	ds_write2_b32 v19, v114, v115 offset1:1
	v_add_u32_e32 v19, 0x14a0, v1
	s_waitcnt vmcnt(2)
	ds_write2_b32 v19, v116, v117 offset1:1
	v_add_u32_e32 v19, 0x14a8, v1
	ds_write2_b32 v19, v118, v119 offset1:1
	v_add_u32_e32 v19, 0x18c0, v1
	s_waitcnt vmcnt(1)
	ds_write2_b32 v19, v120, v121 offset1:1
	v_add_u32_e32 v19, 0x18c8, v1
	ds_write2_b32 v19, v122, v123 offset1:1
	v_add_u32_e32 v19, 0x1ce0, v1
	v_add_u32_e32 v1, 0x1ce8, v1
	s_waitcnt vmcnt(0)
	ds_write2_b32 v19, v124, v125 offset1:1
	ds_write2_b32 v1, v126, v127 offset1:1
	s_waitcnt lgkmcnt(0)
	v_ashrrev_i32_e32 v19, 31, v18
	v_lshl_add_u64 v[2:3], v[18:19], 1, v[2:3]
	ds_read2_b32 v[18:19], v27 offset0:33 offset1:41
	ds_read2_b32 v[36:37], v27 offset1:8
	ds_read2_b32 v[38:39], v27 offset0:66 offset1:74
	ds_read2_b32 v[40:41], v27 offset0:99 offset1:107
	ds_read2_b32 v[42:43], v27 offset0:132 offset1:140
	ds_read2_b32 v[44:45], v27 offset0:165 offset1:173
	ds_read2_b32 v[46:47], v27 offset0:198 offset1:206
	ds_read2_b32 v[48:49], v27 offset0:231 offset1:239
	v_or_b32_e32 v1, v0, v7
	v_mul_i32_i24_e32 v50, 0xb00, v1
	v_lshl_add_u64 v[2:3], v[2:3], 0, v[146:147]
	v_ashrrev_i32_e32 v51, 31, v50
	v_or_b32_e32 v1, v0, v20
	s_waitcnt lgkmcnt(6)
	v_cvt_pk_bf16_f32 v32, v36, v18
	s_waitcnt lgkmcnt(4)
	v_cvt_pk_bf16_f32 v33, v38, v40
	s_waitcnt lgkmcnt(2)
	v_cvt_pk_bf16_f32 v34, v42, v44
	s_waitcnt lgkmcnt(0)
	v_cvt_pk_bf16_f32 v35, v46, v48
	v_lshl_add_u64 v[50:51], v[50:51], 1, v[2:3]
	v_mul_i32_i24_e32 v18, 0xb00, v1
	global_store_dwordx4 v[50:51], v[32:35], off
	v_or_b32_e32 v1, v0, v21
	v_mul_i32_i24_e32 v50, 0xb00, v1
	v_cvt_pk_bf16_f32 v32, v37, v19
	v_ashrrev_i32_e32 v19, 31, v18
	v_cvt_pk_bf16_f32 v33, v39, v41
	v_cvt_pk_bf16_f32 v34, v43, v45
	v_cvt_pk_bf16_f32 v35, v47, v49
	v_lshl_add_u64 v[18:19], v[18:19], 1, v[2:3]
	global_store_dwordx4 v[18:19], v[32:35], off
	ds_read2_b32 v[18:19], v27 offset0:16 offset1:24
	ds_read2_b32 v[36:37], v27 offset0:49 offset1:57
	ds_read2_b32 v[38:39], v27 offset0:82 offset1:90
	ds_read2_b32 v[40:41], v27 offset0:115 offset1:123
	ds_read2_b32 v[42:43], v27 offset0:148 offset1:156
	ds_read2_b32 v[44:45], v27 offset0:181 offset1:189
	ds_read2_b32 v[46:47], v27 offset0:214 offset1:222
	ds_read2_b32 v[48:49], v27 offset0:247 offset1:255
	v_or_b32_e32 v0, v0, v22
	v_ashrrev_i32_e32 v51, 31, v50
	v_mul_i32_i24_e32 v0, 0xb00, v0
	s_waitcnt lgkmcnt(6)
	v_cvt_pk_bf16_f32 v32, v18, v36
	s_waitcnt lgkmcnt(4)
	v_cvt_pk_bf16_f32 v33, v38, v40
	s_waitcnt lgkmcnt(2)
	v_cvt_pk_bf16_f32 v34, v42, v44
	s_waitcnt lgkmcnt(0)
	v_cvt_pk_bf16_f32 v35, v46, v48
	v_lshl_add_u64 v[50:51], v[50:51], 1, v[2:3]
	v_ashrrev_i32_e32 v1, 31, v0
	global_store_dwordx4 v[50:51], v[32:35], off
	v_lshl_add_u64 v[0:1], v[0:1], 1, v[2:3]
	s_nop 0
	v_cvt_pk_bf16_f32 v32, v19, v37
	v_cvt_pk_bf16_f32 v33, v39, v41
	v_cvt_pk_bf16_f32 v34, v43, v45
	v_cvt_pk_bf16_f32 v35, v47, v49
	global_store_dwordx4 v[0:1], v[32:35], off
	s_waitcnt lgkmcnt(0)

; #define LAS __attribute__((address_space(3)))
; DI unsigned pk2(float lo, float hi) { f32x2 v = {lo, hi}; bf16x2_t b = __builtin_convertvector(v, bf16x2_t); return __builtin_bit_cast(unsigned, b); }
; DI void transpose_item_wide(const float* W, int ldw, int K, int src0, bf16* WT, int n0, int k0, LAS float* scr, int lane) {
;     const int c4 = lane & 7, kr = lane >> 3;
; #pragma unroll
;     for (int i = 0; i < 8; ++i) { const int kk = kr + 8 * i; const f32x4 v = *(const f32x4*)(W + (size_t)(k0 + kk) * ldw + src0 + 4 * c4);
;         LAS float* d = scr + kk * 33 + 4 * c4; d[0] = v.x; d[1] = v.y; d[2] = v.z; d[3] = v.w; }
;     asm volatile("s_waitcnt lgkmcnt(0)" ::: "memory");
;     const int c = lane & 7;
; #pragma unroll
;     for (int j = 0; j < 4; ++j) {
;         const int n = (lane >> 3) + 8 * j; const LAS float* sp = scr + (8 * c) * 33 + n;
;         u32x4 o; o.x = pk2(sp[0 * 33], sp[1 * 33]); o.y = pk2(sp[2 * 33], sp[3 * 33]); o.z = pk2(sp[4 * 33], sp[5 * 33]); o.w = pk2(sp[6 * 33], sp[7 * 33]);
;         *(u32x4*)(WT + (size_t)(n0 + n) * K + k0 + 8 * c) = o;
;     }
;     asm volatile("s_waitcnt lgkmcnt(0)" ::: "memory");
; }
; DI void convw_phase(const Args& A, int l, LAS unsigned char* lds, int tid, int bid, int G) {
;     ...
;         if (r < I_GU) {
;             const int f = r / (16 * (NGU / 32)); r -= f * 16 * (NGU / 32);
;             const int kb = r / (NGU / 32), nb = r % (NGU / 32), n0 = nb * 32, pn = n0 >> 8, cc = n0 & 255;
;             const float* src = (cc < 128 ? A.in[I_WG] : A.in[I_WU]) + (size_t)(l * 2 + f) * DM * DFF;
;             transpose_item_wide(src, DFF, DM, 128 * pn + (cc & 127), wgu + (size_t)f * NGU * DM, n0, kb * 64, scr, lane);
;             continue;
.LBB0_268:
	s_andn2_saveexec_b64 s[2:3], s[8:9]
	s_cbranch_execz .LBB0_245
	s_mov_b32 s8, 0x2e8ba2e9
	v_mul_hi_i32 v0, v80, s8
	v_lshrrev_b32_e32 v1, 31, v0
	v_ashrrev_i32_e32 v0, 9, v0
	v_add_u32_e32 v2, v0, v1
	v_mul_i32_i24_e32 v0, 0xfffff500, v2
	v_add_u32_e32 v0, v0, v80
	v_mul_hi_i32 v1, v0, s8
	v_lshrrev_b32_e32 v3, 31, v1
	v_ashrrev_i32_e32 v1, 5, v1
	v_add_u32_e32 v3, v1, v3
	s_movk_i32 s8, 0xb0
	v_mul_lo_u32 v1, v3, s8
	v_sub_u32_e32 v32, v0, v1
	v_and_b32_e32 v0, 4, v32
	v_cmp_eq_u32_e32 vcc, 0, v0
	v_readlane_b32 s8, v253, 28
	v_readlane_b32 s9, v253, 29
	v_cndmask_b32_e64 v146, v215, 64, vcc
	v_add_u32_e32 v18, s23, v2
	v_lshl_add_u64 v[0:1], s[8:9], 0, v[146:147]
	global_load_dwordx2 v[0:1], v[0:1], off
	s_mov_b32 s14, 0xb00000
	v_lshlrev_b32_e32 v31, 5, v32
	v_lshlrev_b32_e32 v146, 2, v4
	v_or_b32_e32 v48, v31, v7
	v_ashrrev_i32_e32 v49, 31, v48
	v_lshlrev_b64 v[48:49], 11, v[48:49]
	s_waitcnt vmcnt(0)
	v_mad_i64_i32 v[18:19], s[8:9], v18, s14, v[0:1]
	v_lshlrev_b32_e32 v0, 4, v32
	v_and_b32_e32 v1, 0x60, v31
	s_movk_i32 s8, 0xff80
	v_and_or_b32 v32, v0, s8, v1
	v_readlane_b32 s8, v251, 63
	v_readlane_b32 s9, v252, 0
	v_ashrrev_i32_e32 v33, 31, v32
	v_lshl_add_u64 v[18:19], v[32:33], 2, v[18:19]
	v_mov_b64_e32 v[0:1], s[8:9]
	v_mad_i64_i32 v[0:1], s[8:9], v2, s14, v[0:1]
	v_lshlrev_b32_e32 v2, 6, v3
	v_lshl_add_u64 v[18:19], v[18:19], 0, v[146:147]
	v_or_b32_e32 v3, v2, v7
	s_movk_i32 s14, 0x2c00
	v_mad_i64_i32 v[32:33], s[8:9], v3, s14, v[18:19]
	global_load_dwordx4 v[96:99], v[32:33], off
	v_or_b32_e32 v128, v2, v20
	v_mad_i64_i32 v[130:131], s[8:9], v128, s14, v[18:19]
	global_load_dwordx4 v[100:103], v[130:131], off
	v_or_b32_e32 v132, v2, v21
	v_mad_i64_i32 v[134:135], s[8:9], v132, s14, v[18:19]
	global_load_dwordx4 v[104:107], v[134:135], off
	v_or_b32_e32 v136, v2, v22
	v_mad_i64_i32 v[138:139], s[8:9], v136, s14, v[18:19]
	global_load_dwordx4 v[108:111], v[138:139], off
	v_or_b32_e32 v140, v2, v23
	v_mad_i64_i32 v[142:143], s[8:9], v140, s14, v[18:19]
	global_load_dwordx4 v[112:115], v[142:143], off
	v_or_b32_e32 v160, v2, v24
	v_mad_i64_i32 v[162:163], s[8:9], v160, s14, v[18:19]
	global_load_dwordx4 v[116:119], v[162:163], off
	v_or_b32_e32 v164, v2, v25
	v_mad_i64_i32 v[166:167], s[8:9], v164, s14, v[18:19]
	global_load_dwordx4 v[120:123], v[166:167], off
	v_or_b32_e32 v168, v2, v26
	v_mad_i64_i32 v[170:171], s[8:9], v168, s14, v[18:19]
	global_load_dwordx4 v[124:127], v[170:171], off
	v_add_u32_e32 v3, v11, v13
	v_add_u32_e32 v36, 0x420, v3
	v_lshlrev_b32_e32 v146, 1, v6
	s_waitcnt vmcnt(7)
	ds_write2_b32 v3, v96, v97 offset1:1
	ds_write2_b32 v3, v98, v99 offset0:2 offset1:3
	s_waitcnt vmcnt(6)
	ds_write2_b32 v36, v100, v101 offset1:1
	v_add_u32_e32 v32, 0x428, v3
	ds_write2_b32 v32, v102, v103 offset1:1
	v_add_u32_e32 v36, 0x840, v3
	s_waitcnt vmcnt(5)
	ds_write2_b32 v36, v104, v105 offset1:1
	v_add_u32_e32 v32, 0x848, v3
	ds_write2_b32 v32, v106, v107 offset1:1
	v_add_u32_e32 v36, 0xc60, v3
	s_waitcnt vmcnt(4)
	ds_write2_b32 v36, v108, v109 offset1:1
	v_add_u32_e32 v32, 0xc68, v3
	ds_write2_b32 v32, v110, v111 offset1:1
	v_add_u32_e32 v36, 0x1080, v3
	s_waitcnt vmcnt(3)
	ds_write2_b32 v36, v112, v113 offset1:1
	v_add_u32_e32 v32, 0x1088, v3
	ds_write2_b32 v32, v114, v115 offset1:1
	v_add_u32_e32 v36, 0x14a0, v3
	s_waitcnt vmcnt(2)
	ds_write2_b32 v36, v116, v117 offset1:1
	v_add_u32_e32 v32, 0x14a8, v3
	ds_write2_b32 v32, v118, v119 offset1:1
	v_add_u32_e32 v36, 0x18c0, v3
	s_waitcnt vmcnt(1)
	ds_write2_b32 v36, v120, v121 offset1:1
	v_add_u32_e32 v32, 0x18c8, v3
	ds_write2_b32 v32, v122, v123 offset1:1
	v_add_u32_e32 v18, 0x1ce0, v3
	v_add_u32_e32 v3, 0x1ce8, v3
	s_waitcnt vmcnt(0)
	ds_write2_b32 v18, v124, v125 offset1:1
	ds_write2_b32 v3, v126, v127 offset1:1
	s_waitcnt lgkmcnt(0)
	ds_read2_b32 v[32:33], v27 offset0:33 offset1:41
	ds_read2_b32 v[34:35], v27 offset1:8
	ds_read2_b32 v[36:37], v27 offset0:66 offset1:74
	ds_read2_b32 v[38:39], v27 offset0:99 offset1:107
	ds_read2_b32 v[40:41], v27 offset0:132 offset1:140
	ds_read2_b32 v[42:43], v27 offset0:165 offset1:173
	ds_read2_b32 v[44:45], v27 offset0:198 offset1:206
	ds_read2_b32 v[46:47], v27 offset0:231 offset1:239
	v_ashrrev_i32_e32 v3, 31, v2
	v_lshl_add_u64 v[0:1], v[2:3], 1, v[0:1]
	v_lshl_add_u64 v[18:19], v[0:1], 0, v[146:147]
	s_waitcnt lgkmcnt(6)
	v_cvt_pk_bf16_f32 v0, v34, v32
	s_waitcnt lgkmcnt(4)
	v_cvt_pk_bf16_f32 v1, v36, v38
	s_waitcnt lgkmcnt(2)
	v_cvt_pk_bf16_f32 v2, v40, v42
	s_waitcnt lgkmcnt(0)
	v_cvt_pk_bf16_f32 v3, v44, v46
	v_lshl_add_u64 v[48:49], v[18:19], 0, v[48:49]
	v_or_b32_e32 v32, v31, v20
	global_store_dwordx4 v[48:49], v[0:3], off
	v_or_b32_e32 v48, v31, v21
	v_ashrrev_i32_e32 v49, 31, v48
	v_cvt_pk_bf16_f32 v0, v35, v33
	v_ashrrev_i32_e32 v33, 31, v32
	v_lshlrev_b64 v[32:33], 11, v[32:33]
	v_cvt_pk_bf16_f32 v1, v37, v39
	v_cvt_pk_bf16_f32 v2, v41, v43
	v_cvt_pk_bf16_f32 v3, v45, v47
	v_lshl_add_u64 v[32:33], v[18:19], 0, v[32:33]
	global_store_dwordx4 v[32:33], v[0:3], off
	ds_read2_b32 v[32:33], v27 offset0:49 offset1:57
	ds_read2_b32 v[34:35], v27 offset0:16 offset1:24
	ds_read2_b32 v[36:37], v27 offset0:82 offset1:90
	ds_read2_b32 v[38:39], v27 offset0:115 offset1:123
	ds_read2_b32 v[40:41], v27 offset0:148 offset1:156
	ds_read2_b32 v[42:43], v27 offset0:181 offset1:189
	ds_read2_b32 v[44:45], v27 offset0:214 offset1:222
	ds_read2_b32 v[46:47], v27 offset0:247 offset1:255
	v_lshlrev_b64 v[48:49], 11, v[48:49]
	s_waitcnt lgkmcnt(6)
	v_cvt_pk_bf16_f32 v0, v34, v32
	s_waitcnt lgkmcnt(4)
	v_cvt_pk_bf16_f32 v1, v36, v38
	s_waitcnt lgkmcnt(2)
	v_cvt_pk_bf16_f32 v2, v40, v42
	s_waitcnt lgkmcnt(0)
	v_cvt_pk_bf16_f32 v3, v44, v46
	v_lshl_add_u64 v[48:49], v[18:19], 0, v[48:49]
	v_or_b32_e32 v32, v31, v22
	global_store_dwordx4 v[48:49], v[0:3], off
	s_nop 1
	v_cvt_pk_bf16_f32 v0, v35, v33
	v_ashrrev_i32_e32 v33, 31, v32
	v_lshlrev_b64 v[32:33], 11, v[32:33]
	v_cvt_pk_bf16_f32 v1, v37, v39
	v_cvt_pk_bf16_f32 v2, v41, v43
	v_cvt_pk_bf16_f32 v3, v45, v47
	v_lshl_add_u64 v[18:19], v[18:19], 0, v[32:33]
	global_store_dwordx4 v[18:19], v[0:3], off
	s_waitcnt lgkmcnt(0)
	s_branch .LBB0_245

; DI float hlo(unsigned u) { return (float)__builtin_bit_cast(f16x2_t, u).x; }
; DI float hhi(unsigned u) { return (float)__builtin_bit_cast(f16x2_t, u).y; }
; DI void lnmod_phase(const Args& A, LAS unsigned char* lds, int tid, int bid, int G, bool init, int l_norm, int i_norm, int l_mod, int i_mod, bool want_dt, int nrows, bool ctx_partial, const float* gprev, const float* bprev) {
;     ...
;         for (int j = 0; j < 4; ++j) v[j] = init ? fn[j] : (f32x4){hlo(un[j].x), hhi(un[j].x), hlo(un[j].y), hhi(un[j].y)};
;         { const int rown = row + G * 8;
;           if (rown < nrows) {
;               if (init) { const float* xin = rown < M_LAT ? A.in[I_X] + (size_t)rown * DM : A.in[I_CTX] + (size_t)(rown - M_LAT) * DM;
; #pragma unroll
;                   for (int j = 0; j < 4; ++j) fn[j] = *(const f32x4*)(xin + 256 * j + 4 * lane); }
;               else {
; #pragma unroll
;                   for (int j = 0; j < 4; ++j) un[j] = *(const u32x2*)(X16 + (size_t)rown * DM + 256 * j + 4 * lane); } } }
;         f32x2* STAT = (f32x2*)(A.ws + WS_STAT);
;         if (ctx_partial && row >= M_LAT) {
.LBB0_282:
	s_or_b64 exec, exec, s[4:5]
	v_cvt_f32_f16_sdwa v104, v90 dst_sel:DWORD dst_unused:UNUSED_PAD src0_sel:WORD_1
	v_cvt_f32_f16_e32 v88, v90
	v_cvt_f32_f16_sdwa v89, v91 dst_sel:DWORD dst_unused:UNUSED_PAD src0_sel:WORD_1
	v_cvt_f32_f16_e32 v105, v91
	v_cvt_f32_f16_sdwa v100, v92 dst_sel:DWORD dst_unused:UNUSED_PAD src0_sel:WORD_1
	v_cvt_f32_f16_e32 v90, v92
	v_cvt_f32_f16_sdwa v91, v93 dst_sel:DWORD dst_unused:UNUSED_PAD src0_sel:WORD_1
	v_cvt_f32_f16_e32 v101, v93
	v_cvt_f32_f16_sdwa v95, v96 dst_sel:DWORD dst_unused:UNUSED_PAD src0_sel:WORD_1
	v_cvt_f32_f16_e32 v94, v96
	v_cvt_f32_f16_sdwa v93, v97 dst_sel:DWORD dst_unused:UNUSED_PAD src0_sel:WORD_1
	v_cvt_f32_f16_e32 v92, v97
	v_cvt_f32_f16_sdwa v102, v86 dst_sel:DWORD dst_unused:UNUSED_PAD src0_sel:WORD_1
	v_cvt_f32_f16_e32 v98, v86
	v_cvt_f32_f16_sdwa v106, v87 dst_sel:DWORD dst_unused:UNUSED_PAD src0_sel:WORD_1
	v_cvt_f32_f16_e32 v96, v87
	s_movk_i32 s4, 0x7fff
	v_cmp_lt_i32_e32 vcc, s4, v84
	v_readlane_b32 s4, v253, 37
	v_readlane_b32 s28, v253, 23
	v_readlane_b32 s5, v253, 38
	v_readlane_b32 s30, v253, 25
	v_readlane_b32 s31, v253, 26
	s_and_b64 s[24:25], s[4:5], vcc
	v_readlane_b32 s29, v253, 24
	v_lshl_add_u64 v[86:87], s[30:31], 0, v[64:65]
	s_and_saveexec_b64 s[4:5], s[24:25]
	s_cbranch_execz .LBB0_284
; DI unsigned pkh2(float lo, float hi) { return __builtin_bit_cast(unsigned, __builtin_amdgcn_cvt_pkrtz(lo, hi)); }
; DI void lnmod_phase(const Args& A, LAS unsigned char* lds, int tid, int bid, int G, bool init, int l_norm, int i_norm, int l_mod, int i_mod, bool want_dt, int nrows, bool ctx_partial, const float* gprev, const float* bprev) {
;     ...
;         if (ctx_partial && row >= M_LAT) {
;             { const f32x2 st = STAT[row];
; #pragma unroll
;               for (int j = 0; j < 4; ++j) v[j] = (v[j] - st.x) * st.y * *(const f32x4*)(gprev + 256 * j + 4 * lane) + *(const f32x4*)(bprev + 256 * j + 4 * lane); }
;             const float* t0 = (const float*)(A.ws + WS_T) + (size_t)(row - M_LAT) * DM; const float* t1 = t0 + (size_t)M_CTX * DM; const float* t2 = t1 + (size_t)M_CTX * DM; const float* t3 = t2 + (size_t)M_CTX * DM;
; #pragma unroll
;             for (int j = 0; j < 4; ++j) { v[j] = v[j] * ALPHA + (*(const f32x4*)(t0 + 256 * j + 4 * lane) + *(const f32x4*)(t1 + 256 * j + 4 * lane)) + (*(const f32x4*)(t2 + 256 * j + 4 * lane) + *(const f32x4*)(t3 + 256 * j + 4 * lane)); u32x2 w_; w_.x = pkh2(v[j].x, v[j].y); w_.y = pkh2(v[j].z, v[j].w); *(u32x2*)(xout + 256 * j + 4 * lane) = w_; }
;         }
	v_readlane_b32 s26, v253, 25
	v_readlane_b32 s27, v253, 26
	v_add_u32_e32 v146, 0xffff8000, v84
	s_nop 1
	v_lshl_add_u64 v[108:109], s[26:27], 0, v[74:75]
	global_load_dwordx2 v[116:117], v[108:109], off
	v_readlane_b32 s24, v251, 61
	v_readlane_b32 s25, v251, 62
	s_mov_b32 s9, 0x800000
	global_load_dwordx4 v[124:127], v[68:69], off
	global_load_dwordx4 v[112:115], v[70:71], off
	global_load_dwordx4 v[128:131], v[68:69], off offset:1024
	global_load_dwordx4 v[132:135], v[70:71], off offset:1024
	global_load_dwordx4 v[136:139], v[68:69], off offset:2048
	global_load_dwordx4 v[140:143], v[70:71], off offset:2048
	global_load_dwordx4 v[154:157], v[68:69], off offset:3072
	global_load_dwordx4 v[160:163], v[70:71], off offset:3072
	s_waitcnt vmcnt(8)
	v_sub_f32_e32 v109, v104, v116
	v_sub_f32_e32 v108, v88, v116
	v_sub_f32_e32 v88, v105, v116
	v_pk_mul_f32 v[104:105], v[116:117], v[108:109] op_sel:[1,0]
	v_sub_f32_e32 v89, v89, v116
	v_pk_mul_f32 v[88:89], v[116:117], v[88:89] op_sel:[1,0]
	v_sub_f32_e32 v91, v91, v116
	v_sub_f32_e32 v95, v95, v116
	v_sub_f32_e32 v94, v94, v116
	v_sub_f32_e32 v93, v93, v116
	v_sub_f32_e32 v92, v92, v116
	v_sub_f32_e32 v99, v102, v116
	v_sub_f32_e32 v98, v98, v116
	v_sub_f32_e32 v97, v106, v116
	v_sub_f32_e32 v96, v96, v116
	v_pk_mul_f32 v[106:107], v[116:117], v[98:99] op_sel:[1,0]
	s_waitcnt vmcnt(6)
	v_pk_fma_f32 v[120:121], v[124:125], v[104:105], v[112:113]
	v_pk_fma_f32 v[88:89], v[126:127], v[88:89], v[114:115]
	v_sub_f32_e32 v105, v100, v116
	v_sub_f32_e32 v104, v90, v116
	v_sub_f32_e32 v90, v101, v116
	v_pk_mul_f32 v[100:101], v[116:117], v[90:91] op_sel:[1,0]
	v_pk_mul_f32 v[90:91], v[116:117], v[104:105] op_sel:[1,0]
	v_pk_mul_f32 v[104:105], v[116:117], v[94:95] op_sel:[1,0]
	s_waitcnt vmcnt(4)
	v_pk_fma_f32 v[90:91], v[90:91], v[128:129], v[132:133]
	v_pk_fma_f32 v[108:109], v[100:101], v[130:131], v[134:135]
	v_pk_mul_f32 v[100:101], v[116:117], v[92:93] op_sel:[1,0]
	s_waitcnt vmcnt(2)
	v_pk_fma_f32 v[136:137], v[104:105], v[136:137], v[140:141]
	v_pk_fma_f32 v[138:139], v[100:101], v[138:139], v[142:143]
	v_pk_mul_f32 v[104:105], v[116:117], v[96:97] op_sel:[1,0]
	s_waitcnt vmcnt(0)
	v_pk_fma_f32 v[154:155], v[106:107], v[154:155], v[160:161]
	v_lshlrev_b64 v[100:101], 12, v[146:147]
	v_lshl_add_u64 v[100:101], s[24:25], 0, v[100:101]
	v_lshlrev_b32_e32 v146, 2, v66
	v_lshl_add_u64 v[106:107], v[100:101], 0, v[146:147]
	v_add_co_u32_e32 v124, vcc, s9, v106
	global_load_dwordx4 v[112:115], v[106:107], off
	s_nop 1
	v_addc_co_u32_e32 v125, vcc, 0, v107, vcc
	global_load_dwordx4 v[116:119], v[124:125], off
	s_mov_b64 s[24:25], 0x800000
	v_lshl_add_u64 v[110:111], v[106:107], 0, s[24:25]
	s_mov_b64 s[24:25], 0x1000000
	v_lshl_add_u64 v[126:127], v[106:107], 0, s[24:25]
	s_mov_b64 s[24:25], 0x1800000
	v_lshl_add_u64 v[128:129], v[106:107], 0, s[24:25]
	s_mov_b32 s9, 0x1000000
	v_add_co_u32_e32 v130, vcc, s9, v106
	s_nop 1
	v_addc_co_u32_e32 v131, vcc, 0, v107, vcc
	s_mov_b32 s9, 0x1800000
	global_load_dwordx4 v[132:135], v[130:131], off
	v_add_co_u32_e32 v140, vcc, s9, v106
	s_nop 1
	v_addc_co_u32_e32 v141, vcc, 0, v107, vcc
	global_load_dwordx4 v[164:167], v[140:141], off
	global_load_dwordx4 v[168:171], v[106:107], off offset:1024
	global_load_dwordx4 v[172:175], v[110:111], off offset:1024
	global_load_dwordx4 v[176:179], v[126:127], off offset:1024
	global_load_dwordx4 v[180:183], v[128:129], off offset:1024
	global_load_dwordx4 v[184:187], v[106:107], off offset:2048
	global_load_dwordx4 v[188:191], v[110:111], off offset:2048
	global_load_dwordx4 v[192:195], v[126:127], off offset:2048
	global_load_dwordx4 v[196:199], v[128:129], off offset:2048
	global_load_dwordx4 v[200:203], v[106:107], off offset:3072
	global_load_dwordx4 v[204:207], v[110:111], off offset:3072
	global_load_dwordx4 v[218:221], v[126:127], off offset:3072
	global_load_dwordx4 v[222:225], v[128:129], off offset:3072
	s_nop 0
	v_pk_fma_f32 v[156:157], v[104:105], v[156:157], v[162:163]
	s_mov_b32 s24, 0x3fd744fd
	s_waitcnt vmcnt(14)
	v_pk_add_f32 v[100:101], v[114:115], v[118:119]
	s_nop 0
	v_pk_fma_f32 v[88:89], v[88:89], s[24:25], v[100:101] op_sel_hi:[1,0,1]
	v_pk_add_f32 v[112:113], v[112:113], v[116:117]
	s_nop 0
	v_pk_fma_f32 v[120:121], v[120:121], s[24:25], v[112:113] op_sel_hi:[1,0,1]
	s_mov_b32 s9, 0x21200000
	s_nop 0
	s_waitcnt vmcnt(12)
	v_pk_add_f32 v[100:101], v[134:135], v[166:167]
	v_pk_add_f32 v[132:133], v[132:133], v[164:165]
	v_pk_add_f32 v[100:101], v[88:89], v[100:101]
	v_pk_add_f32 v[88:89], v[120:121], v[132:133]
	v_add_co_u32_e32 v112, vcc, s9, v86
	v_cvt_pkrtz_f16_f32 v114, v88, v89
	v_cvt_pkrtz_f16_f32 v115, v100, v101
	v_addc_co_u32_e32 v113, vcc, 0, v87, vcc
	global_store_dwordx2 v[112:113], v[114:115], off
	s_nop 0
	s_waitcnt vmcnt(11)
	v_pk_add_f32 v[170:171], v[170:171], v[174:175]
	v_pk_add_f32 v[168:169], v[168:169], v[172:173]
	v_pk_fma_f32 v[108:109], v[108:109], s[24:25], v[170:171] op_sel_hi:[1,0,1]
	v_pk_fma_f32 v[90:91], v[90:91], s[24:25], v[168:169] op_sel_hi:[1,0,1]
	s_waitcnt vmcnt(9)
	v_pk_add_f32 v[178:179], v[178:179], v[182:183]
	v_pk_add_f32 v[176:177], v[176:177], v[180:181]
	v_pk_add_f32 v[122:123], v[108:109], v[178:179]
	v_pk_add_f32 v[90:91], v[90:91], v[176:177]
	v_cvt_pkrtz_f16_f32 v109, v122, v123
	v_cvt_pkrtz_f16_f32 v108, v90, v91
	global_store_dwordx2 v[112:113], v[108:109], off offset:512
	s_waitcnt vmcnt(8)
	v_pk_add_f32 v[108:109], v[186:187], v[190:191]
	v_pk_add_f32 v[184:185], v[184:185], v[188:189]
	v_pk_fma_f32 v[108:109], v[138:139], s[24:25], v[108:109] op_sel_hi:[1,0,1]
	v_pk_fma_f32 v[118:119], v[136:137], s[24:25], v[184:185] op_sel_hi:[1,0,1]
	s_waitcnt vmcnt(6)
	v_pk_add_f32 v[194:195], v[194:195], v[198:199]
	v_pk_add_f32 v[196:197], v[192:193], v[196:197]
	v_pk_add_f32 v[92:93], v[108:109], v[194:195]
	v_pk_add_f32 v[94:95], v[118:119], v[196:197]
	v_cvt_pkrtz_f16_f32 v109, v92, v93
	v_cvt_pkrtz_f16_f32 v108, v94, v95
	global_store_dwordx2 v[112:113], v[108:109], off offset:1024
	s_nop 0
	s_waitcnt vmcnt(5)
	v_pk_add_f32 v[202:203], v[202:203], v[206:207]
	v_pk_add_f32 v[200:201], v[200:201], v[204:205]
	v_pk_fma_f32 v[202:203], v[156:157], s[24:25], v[202:203] op_sel_hi:[1,0,1]
	v_pk_fma_f32 v[200:201], v[154:155], s[24:25], v[200:201] op_sel_hi:[1,0,1]
	s_nop 0
	s_waitcnt vmcnt(3)
	v_pk_add_f32 v[220:221], v[220:221], v[224:225]
	v_pk_add_f32 v[222:223], v[218:219], v[222:223]
	v_pk_add_f32 v[96:97], v[202:203], v[220:221]
	v_pk_add_f32 v[98:99], v[200:201], v[222:223]
	v_cvt_pkrtz_f16_f32 v103, v96, v97
	v_cvt_pkrtz_f16_f32 v102, v98, v99
	global_store_dwordx2 v[112:113], v[102:103], off offset:1536
	v_mov_b32_e32 v104, v89
	v_mov_b32_e32 v105, v100
	v_mov_b32_e32 v89, v101
	v_mov_b32_e32 v100, v91
	v_mov_b32_e32 v101, v122
	v_mov_b32_e32 v91, v123
	v_mov_b32_e32 v102, v99
	v_mov_b32_e32 v106, v97

; DI void attn_unit(LAS unsigned char* lds, int tid, const bf16* __restrict__ P, const bf16* __restrict__ Vt, bf16* MG, int b, int h, int qrow0, int jt0, int jt1,
;                   float lam, float oscale, const float* subg) {
;     ...
;         pbuf = buf; buf = (buf == 2) ? 0 : buf + 1;
.Latt1_qk:
	s_waitcnt lgkmcnt(7)
	v_mfma_f32_32x32x16_bf16 v[80:95], v[192:195], v[112:115], v[64:79]
	s_waitcnt lgkmcnt(6)
	v_mfma_f32_32x32x16_bf16 v[96:111], v[196:199], v[112:115], v[64:79]
	s_waitcnt lgkmcnt(5)
	v_mfma_f32_32x32x16_bf16 v[80:95], v[200:203], v[116:119], v[80:95]
	s_waitcnt lgkmcnt(4)
	v_mfma_f32_32x32x16_bf16 v[96:111], v[204:207], v[116:119], v[96:111]
	s_waitcnt lgkmcnt(3)
	v_mfma_f32_32x32x16_bf16 v[80:95], v[218:221], v[120:123], v[80:95]
	s_waitcnt lgkmcnt(2)
	v_mfma_f32_32x32x16_bf16 v[96:111], v[222:225], v[120:123], v[96:111]
	s_waitcnt lgkmcnt(1)
	v_mfma_f32_32x32x16_bf16 v[80:95], v[226:229], v[124:127], v[80:95]
	s_waitcnt lgkmcnt(0)
	v_mfma_f32_32x32x16_bf16 v[96:111], v[230:233], v[124:127], v[96:111]
	s_add_i32 s2, s19, 1
	s_cmp_lg_u32 s19, 2
	s_cselect_b32 s2, s2, 0
	s_add_i32 s17, s17, 64
	s_mov_b64 s[22:23], 0x80
	s_add_i32 s18, s18, 1
	v_lshl_add_u64 v[162:163], v[162:163], 0, s[22:23]
	v_lshl_add_u64 v[164:165], v[164:165], 0, s[22:23]
	s_nop 5
	v_max3_f32 v145, v80, v81, v82
	v_max3_f32 v146, v96, v97, v98
	v_max3_f32 v145, v145, v83, v84
	v_max3_f32 v146, v146, v99, v100
	v_max3_f32 v145, v145, v85, v86
	v_max3_f32 v146, v146, v101, v102
	v_max3_f32 v145, v145, v87, v88
	v_max3_f32 v146, v146, v103, v104
	v_max3_f32 v145, v145, v89, v90
	v_max3_f32 v146, v146, v105, v106
	v_max3_f32 v145, v145, v91, v92
	v_max3_f32 v146, v146, v107, v108
	v_max3_f32 v145, v145, v93, v94
	v_max3_f32 v146, v146, v109, v110
	v_max3_f32 v145, v145, v95, v111
	v_max_f32_e32 v145, v145, v146
	v_cmp_lt_f32_e32 vcc, 0x41000000, v145
	s_cbranch_vccz .Latt1_nors
	ds_bpermute_b32 v146, v209, v145
	s_waitcnt lgkmcnt(0)
	v_max_f32_e32 v146, v145, v146
	v_cmp_lt_f32_e32 vcc, 0x41000000, v146
	s_nop 0
	s_nop 0
	v_cndmask_b32_e32 v146, 0, v146, vcc
	v_exp_f32_e64 v150, -v146
	v_add_f32_e32 v159, v159, v146
	v_xor_b32_e32 v64, 0x80000000, v159
	v_mov_b32_e32 v65, v64
	v_mov_b32_e32 v66, v64
	v_mov_b32_e32 v67, v64
	v_mov_b32_e32 v68, v64
	v_mov_b32_e32 v69, v64
	v_mov_b32_e32 v70, v64
	v_mov_b32_e32 v71, v64
	v_mov_b32_e32 v72, v64
	v_mov_b32_e32 v73, v64
	v_mov_b32_e32 v74, v64
	v_mov_b32_e32 v75, v64
	v_mov_b32_e32 v76, v64
	v_mov_b32_e32 v77, v64
	v_mov_b32_e32 v78, v64
	v_mov_b32_e32 v79, v64
	v_mul_f32_e32 v158, v158, v150
	v_pk_mul_f32 v[14:15], v[14:15], v[150:151] op_sel_hi:[1,0]
	v_pk_mul_f32 v[12:13], v[12:13], v[150:151] op_sel_hi:[1,0]
	v_pk_mul_f32 v[10:11], v[10:11], v[150:151] op_sel_hi:[1,0]
	v_pk_mul_f32 v[8:9], v[8:9], v[150:151] op_sel_hi:[1,0]
	v_pk_mul_f32 v[6:7], v[6:7], v[150:151] op_sel_hi:[1,0]
	v_pk_mul_f32 v[4:5], v[4:5], v[150:151] op_sel_hi:[1,0]
	v_pk_mul_f32 v[2:3], v[2:3], v[150:151] op_sel_hi:[1,0]
	v_pk_mul_f32 v[0:1], v[0:1], v[150:151] op_sel_hi:[1,0]
	v_pk_mul_f32 v[30:31], v[30:31], v[150:151] op_sel_hi:[1,0]
	v_pk_mul_f32 v[28:29], v[28:29], v[150:151] op_sel_hi:[1,0]
	v_pk_mul_f32 v[26:27], v[26:27], v[150:151] op_sel_hi:[1,0]
	v_pk_mul_f32 v[24:25], v[24:25], v[150:151] op_sel_hi:[1,0]
	v_pk_mul_f32 v[22:23], v[22:23], v[150:151] op_sel_hi:[1,0]
	v_pk_mul_f32 v[20:21], v[20:21], v[150:151] op_sel_hi:[1,0]
	v_pk_mul_f32 v[18:19], v[18:19], v[150:151] op_sel_hi:[1,0]
	v_pk_mul_f32 v[16:17], v[16:17], v[150:151] op_sel_hi:[1,0]
	v_pk_mul_f32 v[46:47], v[46:47], v[150:151] op_sel_hi:[1,0]
	v_pk_mul_f32 v[44:45], v[44:45], v[150:151] op_sel_hi:[1,0]
	v_pk_mul_f32 v[42:43], v[42:43], v[150:151] op_sel_hi:[1,0]
	v_pk_mul_f32 v[40:41], v[40:41], v[150:151] op_sel_hi:[1,0]
	v_pk_mul_f32 v[38:39], v[38:39], v[150:151] op_sel_hi:[1,0]
	v_pk_mul_f32 v[36:37], v[36:37], v[150:151] op_sel_hi:[1,0]
	v_pk_mul_f32 v[34:35], v[34:35], v[150:151] op_sel_hi:[1,0]
	v_pk_mul_f32 v[32:33], v[32:33], v[150:151] op_sel_hi:[1,0]
	v_pk_mul_f32 v[62:63], v[62:63], v[150:151] op_sel_hi:[1,0]
	v_pk_mul_f32 v[60:61], v[60:61], v[150:151] op_sel_hi:[1,0]
	v_pk_mul_f32 v[58:59], v[58:59], v[150:151] op_sel_hi:[1,0]
	v_pk_mul_f32 v[56:57], v[56:57], v[150:151] op_sel_hi:[1,0]
	v_pk_mul_f32 v[54:55], v[54:55], v[150:151] op_sel_hi:[1,0]
	v_pk_mul_f32 v[52:53], v[52:53], v[150:151] op_sel_hi:[1,0]
	v_pk_mul_f32 v[50:51], v[50:51], v[150:151] op_sel_hi:[1,0]
	v_pk_mul_f32 v[48:49], v[48:49], v[150:151] op_sel_hi:[1,0]
	v_pk_add_f32 v[80:81], v[80:81], v[146:147] op_sel_hi:[1,0] neg_lo:[0,1] neg_hi:[0,1]
	v_pk_add_f32 v[96:97], v[96:97], v[146:147] op_sel_hi:[1,0] neg_lo:[0,1] neg_hi:[0,1]
	v_pk_add_f32 v[82:83], v[82:83], v[146:147] op_sel_hi:[1,0] neg_lo:[0,1] neg_hi:[0,1]
	v_pk_add_f32 v[98:99], v[98:99], v[146:147] op_sel_hi:[1,0] neg_lo:[0,1] neg_hi:[0,1]
	v_pk_add_f32 v[84:85], v[84:85], v[146:147] op_sel_hi:[1,0] neg_lo:[0,1] neg_hi:[0,1]
	v_pk_add_f32 v[100:101], v[100:101], v[146:147] op_sel_hi:[1,0] neg_lo:[0,1] neg_hi:[0,1]
	v_pk_add_f32 v[86:87], v[86:87], v[146:147] op_sel_hi:[1,0] neg_lo:[0,1] neg_hi:[0,1]
	v_pk_add_f32 v[102:103], v[102:103], v[146:147] op_sel_hi:[1,0] neg_lo:[0,1] neg_hi:[0,1]
	v_pk_add_f32 v[88:89], v[88:89], v[146:147] op_sel_hi:[1,0] neg_lo:[0,1] neg_hi:[0,1]
	v_pk_add_f32 v[104:105], v[104:105], v[146:147] op_sel_hi:[1,0] neg_lo:[0,1] neg_hi:[0,1]
	v_pk_add_f32 v[90:91], v[90:91], v[146:147] op_sel_hi:[1,0] neg_lo:[0,1] neg_hi:[0,1]
	v_pk_add_f32 v[106:107], v[106:107], v[146:147] op_sel_hi:[1,0] neg_lo:[0,1] neg_hi:[0,1]
	v_pk_add_f32 v[92:93], v[92:93], v[146:147] op_sel_hi:[1,0] neg_lo:[0,1] neg_hi:[0,1]
	v_pk_add_f32 v[108:109], v[108:109], v[146:147] op_sel_hi:[1,0] neg_lo:[0,1] neg_hi:[0,1]
	v_pk_add_f32 v[94:95], v[94:95], v[146:147] op_sel_hi:[1,0] neg_lo:[0,1] neg_hi:[0,1]
	v_pk_add_f32 v[110:111], v[110:111], v[146:147] op_sel_hi:[1,0] neg_lo:[0,1] neg_hi:[0,1]
.Latt1_nors:
	v_exp_f32_e32 v80, v80
	v_exp_f32_e32 v81, v81
	v_exp_f32_e32 v82, v82
	v_exp_f32_e32 v83, v83
	v_exp_f32_e32 v84, v84
	v_exp_f32_e32 v85, v85
	v_exp_f32_e32 v86, v86
	v_exp_f32_e32 v87, v87
	v_add_f32_e32 v145, v80, v81
	v_add_f32_e32 v146, v82, v83
	v_add_f32_e32 v150, v84, v85
	v_add_f32_e32 v151, v86, v87
	v_cvt_pk_bf16_f32 v80, v80, v81
	v_cvt_pk_bf16_f32 v81, v82, v83
	v_cvt_pk_bf16_f32 v82, v84, v85
	v_cvt_pk_bf16_f32 v83, v86, v87
	s_cmpk_eq_i32 s17, 0x10c0
	s_cbranch_scc1 .LBB0_312
	s_mov_b32 s21, s19
	s_branch .LBB0_300

; #define LAS __attribute__((address_space(3)))
; DI unsigned pk2(float lo, float hi) { f32x2 v = {lo, hi}; bf16x2_t b = __builtin_convertvector(v, bf16x2_t); return __builtin_bit_cast(unsigned, b); }
; DI void transpose_item_wide(const float* W, int ldw, int K, int src0, bf16* WT, int n0, int k0, LAS float* scr, int lane) {
;     const int c4 = lane & 7, kr = lane >> 3;
; #pragma unroll
;     for (int i = 0; i < 8; ++i) { const int kk = kr + 8 * i; const f32x4 v = *(const f32x4*)(W + (size_t)(k0 + kk) * ldw + src0 + 4 * c4);
;         LAS float* d = scr + kk * 33 + 4 * c4; d[0] = v.x; d[1] = v.y; d[2] = v.z; d[3] = v.w; }
;     asm volatile("s_waitcnt lgkmcnt(0)" ::: "memory");
;     const int c = lane & 7;
; #pragma unroll
;     for (int j = 0; j < 4; ++j) {
;         const int n = (lane >> 3) + 8 * j; const LAS float* sp = scr + (8 * c) * 33 + n;
;         u32x4 o; o.x = pk2(sp[0 * 33], sp[1 * 33]); o.y = pk2(sp[2 * 33], sp[3 * 33]); o.z = pk2(sp[4 * 33], sp[5 * 33]); o.w = pk2(sp[6 * 33], sp[7 * 33]);
;         *(u32x4*)(WT + (size_t)(n0 + n) * K + k0 + 8 * c) = o;
;     }
;     asm volatile("s_waitcnt lgkmcnt(0)" ::: "memory");
; }
.LBB0_978:
	s_andn2_saveexec_b64 s[4:5], s[4:5]
	s_cbranch_execz .LBB0_955
	s_mov_b32 s6, 0x2e8ba2e9
	v_mul_hi_i32 v0, v7, s6
	v_lshrrev_b32_e32 v1, 31, v0
	v_ashrrev_i32_e32 v0, 9, v0
	v_add_u32_e32 v2, v0, v1
	v_mul_i32_i24_e32 v0, 0xfffff500, v2
	v_add_u32_e32 v0, v0, v7
	v_mul_hi_i32 v1, v0, s6
	v_lshrrev_b32_e32 v3, 31, v1
	v_ashrrev_i32_e32 v1, 5, v1
	v_add_u32_e32 v3, v1, v3
	s_movk_i32 s6, 0xb0
	v_mul_lo_u32 v1, v3, s6
	v_sub_u32_e32 v33, v0, v1
	v_and_b32_e32 v0, 4, v33
	v_cmp_eq_u32_e32 vcc, 0, v0
	s_mov_b32 s8, 0xb00000
	v_lshlrev_b32_e32 v32, 5, v33
	v_cndmask_b32_e64 v146, v215, 64, vcc
	v_lshl_add_u64 v[0:1], s[30:31], 0, v[146:147]
	global_load_dwordx2 v[0:1], v[0:1], off
	v_lshlrev_b32_e32 v146, 2, v4
	v_or_b32_e32 v50, v32, v9
	v_ashrrev_i32_e32 v51, 31, v50
	v_lshlrev_b64 v[50:51], 11, v[50:51]
	s_waitcnt vmcnt(0)
	v_mad_i64_i32 v[18:19], s[6:7], v2, s8, v[0:1]
	v_lshlrev_b32_e32 v0, 4, v33
	v_and_b32_e32 v1, 0x60, v32
	s_movk_i32 s6, 0xff80
	v_and_or_b32 v34, v0, s6, v1
	v_readlane_b32 s6, v251, 63
	v_readlane_b32 s7, v252, 0
	v_ashrrev_i32_e32 v35, 31, v34
	v_lshl_add_u64 v[18:19], v[34:35], 2, v[18:19]
	v_mov_b64_e32 v[0:1], s[6:7]
	v_mad_i64_i32 v[0:1], s[6:7], v2, s8, v[0:1]
	v_lshlrev_b32_e32 v2, 6, v3
	v_lshl_add_u64 v[18:19], v[18:19], 0, v[146:147]
	v_or_b32_e32 v3, v2, v9
	s_movk_i32 s8, 0x2c00
	v_mad_i64_i32 v[34:35], s[6:7], v3, s8, v[18:19]
	global_load_dwordx4 v[96:99], v[34:35], off
	v_or_b32_e32 v128, v2, v22
	v_mad_i64_i32 v[130:131], s[6:7], v128, s8, v[18:19]
	global_load_dwordx4 v[100:103], v[130:131], off
	v_or_b32_e32 v132, v2, v23
	v_mad_i64_i32 v[134:135], s[6:7], v132, s8, v[18:19]
	global_load_dwordx4 v[104:107], v[134:135], off
	v_or_b32_e32 v136, v2, v24
	v_mad_i64_i32 v[138:139], s[6:7], v136, s8, v[18:19]
	global_load_dwordx4 v[108:111], v[138:139], off
	v_or_b32_e32 v140, v2, v25
	v_mad_i64_i32 v[142:143], s[6:7], v140, s8, v[18:19]
	global_load_dwordx4 v[112:115], v[142:143], off
	v_or_b32_e32 v160, v2, v26
	v_mad_i64_i32 v[162:163], s[6:7], v160, s8, v[18:19]
	global_load_dwordx4 v[116:119], v[162:163], off
	v_or_b32_e32 v164, v2, v27
	v_mad_i64_i32 v[166:167], s[6:7], v164, s8, v[18:19]
	global_load_dwordx4 v[120:123], v[166:167], off
	v_or_b32_e32 v168, v2, v28
	v_mad_i64_i32 v[170:171], s[6:7], v168, s8, v[18:19]
	global_load_dwordx4 v[124:127], v[170:171], off
	v_add_u32_e32 v3, v11, v21
	v_lshlrev_b32_e32 v146, 1, v6
	s_waitcnt vmcnt(7)
	ds_write2_b32 v3, v96, v97 offset1:1
	ds_write2_b32 v3, v98, v99 offset0:2 offset1:3
	v_add_u32_e32 v33, 0x420, v3
	s_waitcnt vmcnt(6)
	ds_write2_b32 v33, v100, v101 offset1:1
	v_add_u32_e32 v33, 0x428, v3
	ds_write2_b32 v33, v102, v103 offset1:1
	v_add_u32_e32 v33, 0x840, v3
	s_waitcnt vmcnt(5)
	ds_write2_b32 v33, v104, v105 offset1:1
	v_add_u32_e32 v33, 0x848, v3
	ds_write2_b32 v33, v106, v107 offset1:1
	v_add_u32_e32 v33, 0xc60, v3
	s_waitcnt vmcnt(4)
	ds_write2_b32 v33, v108, v109 offset1:1
	v_add_u32_e32 v33, 0xc68, v3
	ds_write2_b32 v33, v110, v111 offset1:1
	v_add_u32_e32 v33, 0x1080, v3
	s_waitcnt vmcnt(3)
	ds_write2_b32 v33, v112, v113 offset1:1
	v_add_u32_e32 v33, 0x1088, v3
	ds_write2_b32 v33, v114, v115 offset1:1
	v_add_u32_e32 v33, 0x14a0, v3
	s_waitcnt vmcnt(2)
	ds_write2_b32 v33, v116, v117 offset1:1
	v_add_u32_e32 v33, 0x14a8, v3
	ds_write2_b32 v33, v118, v119 offset1:1
	v_add_u32_e32 v33, 0x18c0, v3
	s_waitcnt vmcnt(1)
	ds_write2_b32 v33, v120, v121 offset1:1
	v_add_u32_e32 v33, 0x18c8, v3
	ds_write2_b32 v33, v122, v123 offset1:1
	v_add_u32_e32 v18, 0x1ce0, v3
	v_add_u32_e32 v3, 0x1ce8, v3
	s_waitcnt vmcnt(0)
	ds_write2_b32 v18, v124, v125 offset1:1
	ds_write2_b32 v3, v126, v127 offset1:1
	s_waitcnt lgkmcnt(0)
	ds_read2_b32 v[34:35], v29 offset0:33 offset1:41
	ds_read2_b32 v[36:37], v29 offset1:8
	ds_read2_b32 v[38:39], v29 offset0:66 offset1:74
	ds_read2_b32 v[40:41], v29 offset0:99 offset1:107
	ds_read2_b32 v[42:43], v29 offset0:132 offset1:140
	ds_read2_b32 v[44:45], v29 offset0:165 offset1:173
	ds_read2_b32 v[46:47], v29 offset0:198 offset1:206
	ds_read2_b32 v[48:49], v29 offset0:231 offset1:239
	v_ashrrev_i32_e32 v3, 31, v2
	v_lshl_add_u64 v[0:1], v[2:3], 1, v[0:1]
	v_lshl_add_u64 v[18:19], v[0:1], 0, v[146:147]
	s_waitcnt lgkmcnt(6)
	v_cvt_pk_bf16_f32 v0, v36, v34
	s_waitcnt lgkmcnt(4)
	v_cvt_pk_bf16_f32 v1, v38, v40
	s_waitcnt lgkmcnt(2)
	v_cvt_pk_bf16_f32 v2, v42, v44
	s_waitcnt lgkmcnt(0)
	v_cvt_pk_bf16_f32 v3, v46, v48
	v_lshl_add_u64 v[50:51], v[18:19], 0, v[50:51]
	v_or_b32_e32 v34, v32, v22
	global_store_dwordx4 v[50:51], v[0:3], off
	v_or_b32_e32 v50, v32, v23
	v_ashrrev_i32_e32 v51, 31, v50
	v_cvt_pk_bf16_f32 v0, v37, v35
	v_ashrrev_i32_e32 v35, 31, v34
	v_lshlrev_b64 v[34:35], 11, v[34:35]
	v_cvt_pk_bf16_f32 v1, v39, v41
	v_cvt_pk_bf16_f32 v2, v43, v45
	v_cvt_pk_bf16_f32 v3, v47, v49
	v_lshl_add_u64 v[34:35], v[18:19], 0, v[34:35]
	global_store_dwordx4 v[34:35], v[0:3], off
	ds_read2_b32 v[34:35], v29 offset0:49 offset1:57
	ds_read2_b32 v[36:37], v29 offset0:16 offset1:24
	ds_read2_b32 v[38:39], v29 offset0:82 offset1:90
	ds_read2_b32 v[40:41], v29 offset0:115 offset1:123
	ds_read2_b32 v[42:43], v29 offset0:148 offset1:156
	ds_read2_b32 v[44:45], v29 offset0:181 offset1:189
	ds_read2_b32 v[46:47], v29 offset0:214 offset1:222
	ds_read2_b32 v[48:49], v29 offset0:247 offset1:255
	v_or_b32_e32 v32, v32, v24
	v_lshlrev_b64 v[50:51], 11, v[50:51]
	v_ashrrev_i32_e32 v33, 31, v32
	s_waitcnt lgkmcnt(6)
	v_cvt_pk_bf16_f32 v0, v36, v34
	s_waitcnt lgkmcnt(4)
	v_cvt_pk_bf16_f32 v1, v38, v40
	s_waitcnt lgkmcnt(2)
	v_cvt_pk_bf16_f32 v2, v42, v44
	s_waitcnt lgkmcnt(0)
	v_cvt_pk_bf16_f32 v3, v46, v48
	v_lshl_add_u64 v[50:51], v[18:19], 0, v[50:51]
	v_lshlrev_b64 v[32:33], 11, v[32:33]
	global_store_dwordx4 v[50:51], v[0:3], off
	v_lshl_add_u64 v[18:19], v[18:19], 0, v[32:33]
	s_nop 0
	v_cvt_pk_bf16_f32 v0, v37, v35
	v_cvt_pk_bf16_f32 v1, v39, v41
	v_cvt_pk_bf16_f32 v2, v43, v45
	v_cvt_pk_bf16_f32 v3, v47, v49
	global_store_dwordx4 v[18:19], v[0:3], off
	s_waitcnt lgkmcnt(0)
	s_branch .LBB0_955
